# conv B-operand LDS layout 288B block stride (conflict-free reads) + phase merging: combine with next in-proj, AB/HB with next attn/conv (4 fewer grid barriers)
# speedup vs baseline: 1.0591x; 1.0078x over previous
; #define LAS __attribute__((address_space(3)))
; __global__ void __launch_bounds__(512) fwd_megakernel(Params P) {
;   extern __shared__ __attribute__((aligned(16))) unsigned char shm[];
;   LAS unsigned char* lds = (LAS unsigned char*)shm;
;   cg::grid_group grid = cg::this_grid();
;   if (blockIdx.x == 0 && threadIdx.x == 0) __hip_atomic_store((unsigned*)(P.ws + O_CTR), 0u, __ATOMIC_RELAXED, __HIP_MEMORY_SCOPE_AGENT);
;   for (int ph = P.ph_lo; ph < P.ph_hi; ++ph) {
_Z14fwd_megakernel6Params:
	s_load_dwordx4 s[4:7], s[0:1], 0xc0
	s_mov_b32 s8, s2
	s_load_dwordx2 s[2:3], s[0:1], 0xd0
	v_and_b32_e32 v215, 0x3ff, v0
	v_or_b32_e32 v1, s8, v215
	s_waitcnt lgkmcnt(0)
	v_writelane_b32 v253, s4, 0
	v_cmp_eq_u32_e32 vcc, 0, v1
	s_nop 0
	v_writelane_b32 v253, s5, 1
	v_writelane_b32 v253, s6, 2
	v_writelane_b32 v253, s7, 3
	v_writelane_b32 v253, s2, 4
	s_nop 1
	v_writelane_b32 v253, s3, 5
	s_load_dword s3, s[0:1], 0xd8
	s_add_u32 s2, s0, 0xd8
	s_waitcnt lgkmcnt(0)
	v_writelane_b32 v253, s3, 6
	s_addc_u32 s3, s1, 0
	v_writelane_b32 v253, s2, 7
	s_nop 1
	v_writelane_b32 v253, s3, 8
	v_writelane_b32 v253, s8, 9
	v_writelane_b32 v255, 0, 60
	v_writelane_b32 v255, 1, 59
	v_writelane_b32 v255, 0, 58
	v_writelane_b32 v255, 0, 57
	s_and_saveexec_b64 s[4:5], vcc
	s_cbranch_execz .LBB0_2
	s_load_dwordx4 s[8:11], s[0:1], 0xc0
	v_mov_b32_e32 v1, 0x3f912000
	v_mov_b32_e32 v2, 0
	s_waitcnt lgkmcnt(0)
	global_store_dword v1, v2, s[10:11] sc1

; #define GAS __attribute__((address_space(1)))
; #define LAUNDER_V(x) asm volatile("" : "+v"(x))
; __global__ void __launch_bounds__(512) fwd_megakernel(Params P) {
;     ...
;         const int PH_OUT = 2 + 3 * NSL, c = ph - (PH_OUT + 2);
;         int ng;
;         if (ph == 1) ng = 2; else if (ph < PH_OUT) ng = (s < NSL - 1) ? 3 : 2; else if (ph == PH_OUT) ng = 1; else if (ph == PH_OUT + 1) ng = 0; else ng = (c == 0 || c == NSL) ? 1 : 2;
;         if (ph == PH_OUT + 1) {
;           const GAS float* sp = (const GAS float*)(ws + O_SSQ2); GAS float* r2 = (GAS float*)(ws + O_RSTD2);
;           int t3 = threadIdx.x; LAUNDER_V(t3);
;           for (int row = blockIdx.x * 512 + t3; row < TALL; row += gridDim.x * 512) {
;             float pq[16];
; #pragma unroll
;             for (int q2 = 0; q2 < 16; ++q2) pq[q2] = sp[(size_t)q2 * TALL + row];
;             float sst = 0.f;
; #pragma unroll
;             for (int q2 = 0; q2 < 16; ++q2) sst += pq[q2];
;             r2[row] = rsqrtf(sst * (1.0f / 1024.0f) + 1e-6f); }
;         }
; #pragma nounroll
;         for (int gi = 0; gi < ng; ++gi) {
;           const u16* A; const u16* Bt; int M = TS, N = 1024, K = 1024, mode, slo = 0, shi = 0, sl = 0;
;           if (ph == 1 && gi == 0) { A = (const u16*)(ws + O_H3); Bt = (const u16*)(ws + O_W4); M = NPOS; N = 4096; K = 256; mode = EM_FILT; slo = 0; shi = 1 << 30; }
;           else if (ph == 1 || (ph < PH_OUT && gi == 2)) { sl = (ph == 1) ? 0 : s + 1; A = (const u16*)(ws + O_XB) + (size_t)sl * TS * DM; Bt = (const u16*)(ws + O_WIN); N = INW; mode = EM_INPROJ; slo = 18; shi = 30; }
;           else if (ph < PH_OUT && gi == 0) { sl = s; A = (const u16*)(ws + O_ATT); Bt = (const u16*)(ws + O_WAB); K = 512; mode = EM_AB; }
;           else if (ph < PH_OUT) { sl = s; A = (const u16*)(ws + O_ZR); Bt = (const u16*)(ws + O_WHB); mode = EM_HBR; }
;           else if (ph == PH_OUT) { A = (const u16*)(ws + O_MG); Bt = (const u16*)(ws + O_WOUT); M = TALL; mode = EM_OUT; }
;           else if ((c > 0 && gi == 0) || c == NSL) { sl = c - 1; A = (const u16*)(ws + O_HB + (size_t)(sl & 1) * HB_BYTES); Bt = (const u16*)(ws + O_WF2); K = DFF; mode = EM_FF2; }
;           else { sl = c; A = (const u16*)(ws + O_X2B) + (size_t)sl * TS * DM; Bt = (const u16*)(ws + O_WF1); N = DFF; mode = EM_FF1; }
;           run_gemm(P, lds, A, Bt, M, N, K, mode, sl, slo, shi);
.LBB0_26:
	v_readlane_b32 s0, v255, 58
	s_nop 0
	s_cmp_eq_u32 s0, 1
	s_cbranch_scc0 .Lsch_nocap
	s_mov_b32 s82, 2
.Lsch_nocap:
	s_cmp_eq_u32 s82, 0
	s_cbranch_scc1 .LBB0_352
	s_cmp_lg_u32 s72, 17
	s_cselect_b64 s[0:1], -1, 0
	v_writelane_b32 v254, s0, 46
	s_cmp_gt_u32 s72, 19
	v_readlane_b32 s83, v255, 57
	v_writelane_b32 v254, s1, 47
	s_cselect_b64 s[0:1], -1, 0
	v_writelane_b32 v254, s0, 48
	s_cmp_eq_u32 s10, 5
	s_nop 0
	v_writelane_b32 v254, s1, 49
	s_cselect_b64 s[0:1], -1, 0
	v_writelane_b32 v254, s0, 50
	s_nop 1
	v_writelane_b32 v254, s1, 51
	s_mov_b32 s0, s10
	v_readlane_b32 s6, v254, 10
	v_readlane_b32 s7, v254, 11
	s_add_u32 s2, s6, 0xc300000
	s_addc_u32 s3, s7, 0
	s_ashr_i32 s11, s10, 31
	v_writelane_b32 v254, s0, 52
	s_nop 1
	v_writelane_b32 v254, s1, 53
	s_lshl_b64 s[0:1], s[10:11], 25
	s_add_u32 s0, s2, s0
	v_writelane_b32 v254, s0, 54
	s_addc_u32 s0, s3, s1
	v_writelane_b32 v254, s0, 55
	s_sub_i32 s0, s72, 20
	v_writelane_b32 v254, s0, 56
	s_lshl_b32 s0, s72, 27
	s_and_b32 s0, s0, 0x8000000
	s_add_u32 s0, s6, s0
	s_addc_u32 s1, s7, 0
	s_add_u32 s0, s0, 0x16852000
	v_writelane_b32 v254, s0, 57
	s_addc_u32 s0, s1, 0
	v_writelane_b32 v254, s0, 58
	s_add_u32 s0, s6, 0x35912000
	s_addc_u32 s1, s7, 0
	v_writelane_b32 v254, s0, 59
	s_nop 1
	v_writelane_b32 v254, s1, 60
	s_add_u32 s0, s6, 0x1600000
	s_addc_u32 s1, s7, 0
	v_writelane_b32 v254, s0, 61
	s_nop 1
	v_writelane_b32 v254, s1, 62
	s_add_u32 s0, s6, 0x33912000
	s_addc_u32 s1, s7, 0
	v_writelane_b32 v254, s0, 63
	s_nop 1
	v_writelane_b32 v255, s1, 0
	s_add_u32 s0, s6, 0x1400000
	s_addc_u32 s1, s7, 0
	v_writelane_b32 v255, s0, 1
	s_nop 1
	v_writelane_b32 v255, s1, 2
	s_add_u32 s0, s6, 0x30912000
	s_addc_u32 s1, s7, 0
	v_writelane_b32 v255, s0, 3
	s_nop 1
	v_writelane_b32 v255, s1, 4
	s_add_u32 s0, s6, 0x1300000
	s_addc_u32 s1, s7, 0
	v_writelane_b32 v255, s0, 5
	s_nop 1
	v_writelane_b32 v255, s1, 6
	v_readlane_b32 s0, v254, 12
	s_add_i32 s4, s0, 1
	s_and_b64 s[0:1], exec, s[80:81]
	s_cselect_b32 s4, 0, s4
	s_mov_b32 s0, s4
	s_ashr_i32 s5, s4, 31
	v_writelane_b32 v255, s0, 7
	s_nop 1
	v_writelane_b32 v255, s1, 8
	s_lshl_b64 s[0:1], s[4:5], 25
	s_add_u32 s0, s2, s0
	s_addc_u32 s1, s3, s1
	v_writelane_b32 v255, s0, 9
	s_nop 1
	v_writelane_b32 v255, s1, 10
	s_add_u32 s0, s6, 0x2a00000
	s_addc_u32 s1, s7, 0
	v_writelane_b32 v254, s0, 28
	v_writelane_b32 v255, s80, 11
	s_nop 0
	v_writelane_b32 v254, s1, 29
	s_add_u32 s0, s6, 0x2800000
	s_addc_u32 s1, s7, 0
	v_writelane_b32 v254, s0, 32
	v_writelane_b32 v255, s81, 12
	s_nop 0
	v_writelane_b32 v254, s1, 33
	v_writelane_b32 v254, s14, 26
	s_nop 1
	v_writelane_b32 v254, s15, 27
	v_writelane_b32 v254, s82, 34
	s_branch .LBB0_30

; #define LAS __attribute__((address_space(3)))
; #define LAUNDER_V(x) asm volatile("" : "+v"(x))
; #define LAUNDER_S(x) asm volatile("" : "+s"(x))
; __device__ __forceinline__ unsigned pk2(float lo, float hi) { const f32x2_t f = {lo, hi}; const bf16x2_t b = __builtin_convertvector(f, bf16x2_t); return __builtin_bit_cast(unsigned, b); }
; __device__ __forceinline__ void conv_item(const Params& P, int slice, int item, LAS unsigned char* lds) {
;   unsigned char* ws = P.ws; LAUNDER_S(ws); int tid = threadIdx.x; LAUNDER_V(tid);
;   const int wave = __builtin_amdgcn_readfirstlane(tid >> 6), lane = tid & 63, chh = wave >> 2, w4 = wave & 3, wm = w4 & 1, wn = (w4 >> 1) ^ chh  , ht = tid & 255, l16 = lane & 15, kc = lane >> 4;
;   const int c = item * 2 + chh;
;   const int L = slice < 4 ? 2048 : 16384, nb = slice < 4 ? 8 : 1, nblk = 128 / nb, nbsh = slice < 4 ? 3 : 0;
;   const u16* hyT = (const u16*)(ws + O_HYT);
;   LAS unsigned char* Zs = lds + chh * ZS_BYTES;
;   LAS unsigned char* Wn = lds + 2 * ZS_BYTES + chh * 2 * CONV_GRP * WIN_BYTES;
;   const float* wsh = P.in[I_WSH]; const float* bsh = P.in[I_BSH];
;   if (tid < 64) *(LAS unsigned*)(lds + CONV_ZERO_OFF + 4 * tid) = 0u;
;   {
;     const u16* row = hyT + (size_t)c * TS; const float w0 = wsh[c], w1 = wsh[3072 + c], w2 = wsh[6144 + c], bb = bsh[c];
; #pragma unroll
;     for (int hh = 0; hh < 2; ++hh) {
;       Sc4Raw zr[4][2];
; #pragma unroll
;       for (int i4 = 0; i4 < 4; ++i4) { const int tok = 8 * (ht + 256 * (4 * hh + i4)); zr[i4][0] = sc4_load(row, tok); zr[i4][1] = sc4_load(row, tok + 4); }
;       __builtin_amdgcn_sched_barrier(0);
; #pragma unroll
;       for (int i4 = 0; i4 < 4; ++i4) {
;         const int tok = 8 * (ht + 256 * (4 * hh + i4));
;         const f32x4 a = sc4_apply(zr[i4][0], tok, L, w0, w1, w2, bb), bq = sc4_apply(zr[i4][1], tok + 4, L, w0, w1, w2, bb);
;         const int Bk = tok >> 7, bs = Bk / nblk;
;         u32x4 o; o.x = pk2(a[0], a[1]); o.y = pk2(a[2], a[3]); o.z = pk2(bq[0], bq[1]); o.w = pk2(bq[2], bq[3]);
;         *(LAS u32x4*)(Zs + Bk * ZBLK + bs * 32 + 2 * (tok & 127)) = o;
.LBB0_382:
	s_cmpk_gt_i32 s2, 0x2ff
	s_mov_b64 s[0:1], -1
	s_cbranch_scc0 .LBB0_523
	s_movk_i32 s85, 0x120
	v_readlane_b32 s4, v253, 0
	v_readlane_b32 s6, v253, 2
	v_readlane_b32 s7, v253, 3
	s_mov_b64 s[0:1], s[6:7]
	v_mov_b32_e32 v9, v215
	v_readlane_b32 s5, v253, 1
	s_nop 0
	v_readfirstlane_b32 s3, v9
	v_cmp_gt_i32_e32 vcc, 64, v9
	s_and_saveexec_b64 s[4:5], vcc
	v_lshl_add_u32 v0, v9, 2, 0
	v_add_u32_e32 v0, 0x24400, v0
	ds_write_b32 v0, v81
	s_or_b64 exec, exec, s[4:5]
	s_ashr_i32 s4, s3, 8
	s_and_b32 s18, s3, 64
	s_bfe_u32 s3, s3, 0x10007
	s_xor_b32 s8, s3, s4
	s_lshl_b32 s3, s2, 1
	s_add_i32 s3, s3, s4
	s_add_i32 s12, s3, 0xfffffa00
	s_add_u32 s19, s0, 0x1f852000
	s_mul_i32 s16, s4, 0x9200
	s_mul_i32 s4, s4, 0x9000
	s_addc_u32 s20, s1, 0
	s_add_i32 s3, s4, 0
	s_ashr_i32 s13, s12, 31
	s_add_i32 s21, s16, 0
	s_add_i32 s3, s3, 0x12400
	s_lshl_b64 s[6:7], s[12:13], 15
	s_add_u32 s4, s19, s6
	s_addc_u32 s5, s20, s7
	s_lshl_b64 s[10:11], s[12:13], 2
	s_add_u32 s14, s52, s10
	v_mov_b32_e32 v0, 3
	s_addc_u32 s15, s53, s11
	v_lshlrev_b32_sdwa v42, v0, v9 dst_sel:DWORD dst_unused:UNUSED_PAD src0_sel:DWORD src1_sel:BYTE_0
	v_mov_b32_e32 v0, 4
	s_add_u32 s10, s54, s10
	s_waitcnt lgkmcnt(0)
	v_lshlrev_b32_sdwa v80, v0, v9 dst_sel:DWORD dst_unused:UNUSED_PAD src0_sel:DWORD src1_sel:BYTE_0
	v_max_u32_e32 v0, 1, v42
	s_addc_u32 s11, s55, s11
	v_lshl_add_u64 v[12:13], s[4:5], 0, v[80:81]
	v_lshlrev_b32_e32 v0, 1, v0
	s_movk_i32 s9, 0x1000
	global_load_dword v5, v81, s[14:15]
	global_load_dword v4, v220, s[14:15]
	global_load_dword v6, v221, s[14:15]
	global_load_dword v8, v81, s[10:11]
	global_load_dwordx4 v[18:21], v80, s[4:5]
	global_load_ushort v30, v0, s[4:5] offset:-2
	global_load_ushort v32, v80, s[4:5] offset:8
	global_load_ushort v38, v80, s[4:5] offset:16
	v_add_co_u32_e32 v0, vcc, s9, v12
	s_movk_i32 s9, 0x2000
	s_nop 0
	v_addc_co_u32_e32 v1, vcc, 0, v13, vcc
	v_add_co_u32_e32 v10, vcc, s9, v12
	s_movk_i32 s9, 0x3000
	s_nop 0
	v_addc_co_u32_e32 v11, vcc, 0, v13, vcc
	global_load_dwordx4 v[22:25], v[10:11], off offset:-4096
	global_load_ushort v43, v80, s[4:5] offset:4094
	global_load_ushort v44, v[0:1], off offset:8
	global_load_ushort v45, v[0:1], off offset:16
	global_load_dwordx4 v[26:29], v[10:11], off
	global_load_ushort v46, v[0:1], off offset:4094
	global_load_ushort v47, v[10:11], off offset:8
	global_load_ushort v48, v[10:11], off offset:16
	v_add_co_u32_e32 v14, vcc, s9, v12
	s_movk_i32 s9, 0x4000
	s_nop 0
	v_addc_co_u32_e32 v15, vcc, 0, v13, vcc
	v_add_co_u32_e32 v16, vcc, s9, v12
	s_mov_b32 s17, 0
	s_nop 0
	v_addc_co_u32_e32 v17, vcc, 0, v13, vcc
	global_load_dwordx4 v[0:3], v[16:17], off offset:-4096
	global_load_ushort v49, v[10:11], off offset:4094
	global_load_ushort v50, v[14:15], off offset:8
	global_load_ushort v51, v[14:15], off offset:16
	v_lshlrev_b32_e32 v10, 4, v9
	v_and_b32_e32 v7, 48, v9
	v_and_b32_e32 v11, 0xf0, v10
	s_waitcnt vmcnt(0)
	v_lshlrev_b32_e32 v10, 16, v18
	v_lshlrev_b32_e32 v30, 16, v30
	v_cmp_ne_u32_sdwa vcc, v9, v81 src0_sel:BYTE_0 src1_sel:DWORD
	v_and_b32_e32 v18, 0xffff0000, v18
	v_and_b32_e32 v31, 0xffff0000, v19
	v_cndmask_b32_e32 v33, 0, v30, vcc
	v_lshlrev_b32_e32 v35, 16, v32
	v_lshlrev_b32_e32 v19, 16, v19
	v_mov_b32_e32 v32, v18
	v_mov_b32_e32 v30, v19
	v_pk_mul_f32 v[32:33], v[4:5], v[32:33]
	v_pk_mul_f32 v[36:37], v[4:5], v[30:31] op_sel_hi:[0,1]
	v_pk_fma_f32 v[32:33], v[4:5], v[10:11], v[32:33] op_sel:[0,0,1] op_sel_hi:[1,0,0]
	v_mov_b32_e32 v10, v5
	v_mov_b32_e32 v34, v31
	v_pk_fma_f32 v[32:33], v[6:7], v[18:19], v[32:33] op_sel_hi:[0,1,1]
	v_pk_fma_f32 v[18:19], v[10:11], v[18:19], v[36:37] op_sel_hi:[0,1,1]
	v_pk_fma_f32 v[18:19], v[6:7], v[34:35], v[18:19] op_sel_hi:[0,1,1]
	v_pk_add_f32 v[34:35], v[8:9], v[18:19] op_sel_hi:[0,1]
	v_add_u32_e32 v18, 8, v42
	v_and_b32_e32 v18, s33, v18
	v_and_b32_e32 v19, 0xffff0000, v21
	v_lshlrev_b32_e32 v30, 16, v38
	v_cmp_ne_u32_e32 vcc, 0, v18
	v_and_b32_e32 v39, 16, v21
	v_and_b32_e32 v38, 0xffff0000, v20
	v_lshlrev_b32_e32 v41, 16, v21
	v_lshlrev_b32_e32 v21, 16, v20
	v_mov_b32_e32 v20, v31
	v_cndmask_b32_e32 v37, 0, v30, vcc
	v_pk_mov_b32 v[30:31], v[20:21], v[38:39] op_sel:[1,0]
	v_mov_b32_e32 v18, v41
	v_pk_mul_f32 v[30:31], v[4:5], v[30:31] op_sel_hi:[0,1]
	v_mov_b32_e32 v40, v38
	v_pk_fma_f32 v[20:21], v[10:11], v[20:21], v[30:31] op_sel_hi:[0,1,1]
	v_pk_mul_f32 v[30:31], v[4:5], v[18:19] op_sel_hi:[0,1]
	v_pk_fma_f32 v[30:31], v[10:11], v[40:41], v[30:31] op_sel_hi:[0,1,1]
	v_mov_b32_e32 v36, v19
	v_pk_fma_f32 v[20:21], v[6:7], v[40:41], v[20:21] op_sel_hi:[0,1,1]
	v_pk_fma_f32 v[18:19], v[6:7], v[36:37], v[30:31] op_sel_hi:[0,1,1]
	v_pk_add_f32 v[20:21], v[8:9], v[20:21] op_sel_hi:[0,1]
	v_pk_add_f32 v[30:31], v[8:9], v[18:19] op_sel_hi:[0,1]
	v_bfe_u32 v36, v9, 4, 4
	s_movk_i32 s9, 0x100
	v_pk_add_f32 v[32:33], v[8:9], v[32:33] op_sel_hi:[0,1]
	v_cvt_pk_bf16_f32 v20, v20, v21
	v_cvt_pk_bf16_f32 v21, v30, v31
	v_mul_u32_u24_e32 v30, 0x120, v36
	v_or_b32_sdwa v38, v9, s9 dst_sel:DWORD dst_unused:UNUSED_PAD src0_sel:BYTE_0 src1_sel:DWORD
	v_cvt_pk_bf16_f32 v18, v32, v33
	v_cvt_pk_bf16_f32 v19, v34, v35
	v_add3_u32 v30, s21, v30, v11
	v_lshlrev_b32_e32 v34, 3, v38
	ds_write_b128 v30, v[18:21]
	v_and_b32_e32 v19, s33, v34
	v_lshlrev_b32_e32 v18, 16, v22
	v_lshlrev_b32_e32 v20, 16, v43
	v_cmp_ne_u32_e32 vcc, 0, v19
	v_and_b32_e32 v22, 0xffff0000, v22
	v_and_b32_e32 v21, 0xffff0000, v23
	v_cndmask_b32_e32 v31, 0, v20, vcc
	v_lshlrev_b32_e32 v23, 16, v23
	v_mov_b32_e32 v30, v22
	v_mov_b32_e32 v20, v23
	v_pk_mul_f32 v[30:31], v[4:5], v[30:31]
	v_and_b32_e32 v35, 16, v25
	v_pk_fma_f32 v[18:19], v[4:5], v[18:19], v[30:31] op_sel:[0,0,1] op_sel_hi:[1,0,0]
; #define LAS __attribute__((address_space(3)))
; __device__ __forceinline__ unsigned pk2(float lo, float hi) { const f32x2_t f = {lo, hi}; const bf16x2_t b = __builtin_convertvector(f, bf16x2_t); return __builtin_bit_cast(unsigned, b); }
; __device__ __forceinline__ void conv_item(const Params& P, int slice, int item, LAS unsigned char* lds) {
;     ...
; #pragma unroll
;     for (int hh = 0; hh < 2; ++hh) {
;       Sc4Raw zr[4][2];
; #pragma unroll
;       for (int i4 = 0; i4 < 4; ++i4) { const int tok = 8 * (ht + 256 * (4 * hh + i4)); zr[i4][0] = sc4_load(row, tok); zr[i4][1] = sc4_load(row, tok + 4); }
;       __builtin_amdgcn_sched_barrier(0);
; #pragma unroll
;       for (int i4 = 0; i4 < 4; ++i4) {
;         const int tok = 8 * (ht + 256 * (4 * hh + i4));
;         const f32x4 a = sc4_apply(zr[i4][0], tok, L, w0, w1, w2, bb), bq = sc4_apply(zr[i4][1], tok + 4, L, w0, w1, w2, bb);
;         const int Bk = tok >> 7, bs = Bk / nblk;
;         u32x4 o; o.x = pk2(a[0], a[1]); o.y = pk2(a[2], a[3]); o.z = pk2(bq[0], bq[1]); o.w = pk2(bq[2], bq[3]);
;         *(LAS u32x4*)(Zs + Bk * ZBLK + bs * 32 + 2 * (tok & 127)) = o;
	v_pk_mul_f32 v[30:31], v[4:5], v[20:21] op_sel_hi:[0,1]
	v_add_u32_e32 v20, 8, v34
	v_pk_fma_f32 v[18:19], v[6:7], v[22:23], v[18:19] op_sel_hi:[0,1,1]
	v_pk_fma_f32 v[22:23], v[10:11], v[22:23], v[30:31] op_sel_hi:[0,1,1]
	v_and_b32_e32 v31, 0xffff0000, v25
	v_and_b32_e32 v20, s33, v20
	v_and_b32_e32 v34, 0xffff0000, v24
	v_lshlrev_b32_e32 v37, 16, v25
	v_lshlrev_b32_e32 v25, 16, v24
	v_mov_b32_e32 v24, v21
	v_mov_b32_e32 v32, v21
	v_cmp_ne_u32_e32 vcc, 0, v20
	v_pk_mov_b32 v[20:21], v[24:25], v[34:35] op_sel:[1,0]
	v_lshlrev_b32_e32 v33, 16, v44
	v_pk_mul_f32 v[20:21], v[4:5], v[20:21] op_sel_hi:[0,1]
	v_lshlrev_b32_e32 v30, 16, v45
	v_mov_b32_e32 v36, v34
	v_pk_fma_f32 v[20:21], v[10:11], v[24:25], v[20:21] op_sel_hi:[0,1,1]
	v_pk_fma_f32 v[22:23], v[6:7], v[32:33], v[22:23] op_sel_hi:[0,1,1]
	v_cndmask_b32_e32 v33, 0, v30, vcc
	v_mov_b32_e32 v30, v37
	v_pk_fma_f32 v[20:21], v[6:7], v[36:37], v[20:21] op_sel_hi:[0,1,1]
	v_pk_add_f32 v[24:25], v[8:9], v[20:21] op_sel_hi:[0,1]
	v_pk_mul_f32 v[20:21], v[4:5], v[30:31] op_sel_hi:[0,1]
	v_pk_fma_f32 v[20:21], v[10:11], v[36:37], v[20:21] op_sel_hi:[0,1,1]
	v_mov_b32_e32 v32, v31
	v_pk_add_f32 v[18:19], v[8:9], v[18:19] op_sel_hi:[0,1]
	v_pk_fma_f32 v[20:21], v[6:7], v[32:33], v[20:21] op_sel_hi:[0,1,1]
	v_lshrrev_b32_e32 v32, 4, v38
	v_pk_add_f32 v[22:23], v[8:9], v[22:23] op_sel_hi:[0,1]
	v_pk_add_f32 v[30:31], v[8:9], v[20:21] op_sel_hi:[0,1]
	v_lshrrev_b32_e32 v33, s86, v32
	v_cvt_pk_bf16_f32 v20, v18, v19
	v_mov_b32_e32 v18, s21
	v_cvt_pk_bf16_f32 v21, v22, v23
	v_cvt_pk_bf16_f32 v22, v24, v25
	v_mad_u32_u24 v19, v32, s85, v18
	v_lshlrev_b32_e32 v24, 6, v33
	v_cvt_pk_bf16_f32 v23, v30, v31
	v_add3_u32 v19, v19, v24, v11
	s_movk_i32 s9, 0x200
	ds_write_b128 v19, v[20:23]
	v_or_b32_sdwa v19, v9, s9 dst_sel:DWORD dst_unused:UNUSED_PAD src0_sel:BYTE_0 src1_sel:DWORD
	v_lshlrev_b32_e32 v32, 3, v19
	v_and_b32_e32 v21, s33, v32
	v_lshlrev_b32_e32 v20, 16, v26
	v_lshlrev_b32_e32 v22, 16, v46
	v_cmp_ne_u32_e32 vcc, 0, v21
	v_and_b32_e32 v26, 0xffff0000, v26
	v_and_b32_e32 v23, 0xffff0000, v27
	v_cndmask_b32_e32 v25, 0, v22, vcc
	v_lshlrev_b32_e32 v27, 16, v27
	v_mov_b32_e32 v24, v26
	v_mov_b32_e32 v22, v27
	v_pk_mul_f32 v[24:25], v[4:5], v[24:25]
	v_and_b32_e32 v33, 16, v29
	v_pk_fma_f32 v[20:21], v[4:5], v[20:21], v[24:25] op_sel:[0,0,1] op_sel_hi:[1,0,0]
	v_pk_mul_f32 v[24:25], v[4:5], v[22:23] op_sel_hi:[0,1]
	v_add_u32_e32 v22, 8, v32
	v_pk_fma_f32 v[20:21], v[6:7], v[26:27], v[20:21] op_sel_hi:[0,1,1]
	v_pk_fma_f32 v[24:25], v[10:11], v[26:27], v[24:25] op_sel_hi:[0,1,1]
	v_and_b32_e32 v27, 0xffff0000, v29
	v_and_b32_e32 v22, s33, v22
	v_and_b32_e32 v32, 0xffff0000, v28
	v_lshlrev_b32_e32 v35, 16, v29
	v_lshlrev_b32_e32 v29, 16, v28
	v_mov_b32_e32 v28, v23
	v_lshlrev_b32_e32 v31, 16, v47
	v_mov_b32_e32 v30, v23
	v_lshlrev_b32_e32 v26, 16, v48
	v_cmp_ne_u32_e32 vcc, 0, v22
	v_pk_mov_b32 v[22:23], v[28:29], v[32:33] op_sel:[1,0]
	v_pk_fma_f32 v[24:25], v[6:7], v[30:31], v[24:25] op_sel_hi:[0,1,1]
	v_cndmask_b32_e32 v31, 0, v26, vcc
	v_mov_b32_e32 v26, v35
	v_pk_mul_f32 v[22:23], v[4:5], v[22:23] op_sel_hi:[0,1]
	v_mov_b32_e32 v34, v32
	v_pk_fma_f32 v[22:23], v[10:11], v[28:29], v[22:23] op_sel_hi:[0,1,1]
	v_pk_mul_f32 v[28:29], v[4:5], v[26:27] op_sel_hi:[0,1]
	v_pk_fma_f32 v[28:29], v[10:11], v[34:35], v[28:29] op_sel_hi:[0,1,1]
	v_mov_b32_e32 v30, v27
	v_lshrrev_b32_e32 v19, 4, v19
	v_pk_add_f32 v[20:21], v[8:9], v[20:21] op_sel_hi:[0,1]
	v_pk_add_f32 v[24:25], v[8:9], v[24:25] op_sel_hi:[0,1]
	v_pk_fma_f32 v[22:23], v[6:7], v[34:35], v[22:23] op_sel_hi:[0,1,1]
	v_pk_fma_f32 v[26:27], v[6:7], v[30:31], v[28:29] op_sel_hi:[0,1,1]
	v_lshrrev_b32_e32 v28, s86, v19
	v_pk_add_f32 v[22:23], v[8:9], v[22:23] op_sel_hi:[0,1]
	v_pk_add_f32 v[26:27], v[8:9], v[26:27] op_sel_hi:[0,1]
	v_cvt_pk_bf16_f32 v20, v20, v21
	v_cvt_pk_bf16_f32 v21, v24, v25
	v_mad_u32_u24 v19, v19, s85, v18
	v_lshlrev_b32_e32 v24, 6, v28
	v_cvt_pk_bf16_f32 v22, v22, v23
	v_cvt_pk_bf16_f32 v23, v26, v27
	v_add3_u32 v19, v19, v24, v11
	s_movk_i32 s9, 0x300
	ds_write_b128 v19, v[20:23]
	v_or_b32_sdwa v19, v9, s9 dst_sel:DWORD dst_unused:UNUSED_PAD src0_sel:BYTE_0 src1_sel:DWORD
	v_lshlrev_b32_e32 v28, 3, v19
	v_and_b32_e32 v21, s33, v28
	v_lshlrev_b32_e32 v20, 16, v0
	v_lshlrev_b32_e32 v22, 16, v49
	v_cmp_ne_u32_e32 vcc, 0, v21
	v_and_b32_e32 v0, 0xffff0000, v0
	v_and_b32_e32 v23, 0xffff0000, v1
	v_cndmask_b32_e32 v25, 0, v22, vcc
	v_lshlrev_b32_e32 v1, 16, v1
	v_mov_b32_e32 v24, v0
	v_mov_b32_e32 v22, v1
	v_pk_mul_f32 v[24:25], v[4:5], v[24:25]
	v_lshlrev_b32_e32 v27, 16, v50
	v_pk_fma_f32 v[20:21], v[4:5], v[20:21], v[24:25] op_sel:[0,0,1] op_sel_hi:[1,0,0]
	v_pk_mul_f32 v[24:25], v[4:5], v[22:23] op_sel_hi:[0,1]
	v_mov_b32_e32 v26, v23
	v_pk_fma_f32 v[20:21], v[6:7], v[0:1], v[20:21] op_sel_hi:[0,1,1]
	v_pk_fma_f32 v[0:1], v[10:11], v[0:1], v[24:25] op_sel_hi:[0,1,1]
	v_pk_fma_f32 v[0:1], v[6:7], v[26:27], v[0:1] op_sel_hi:[0,1,1]
	v_pk_add_f32 v[24:25], v[8:9], v[0:1] op_sel_hi:[0,1]
	v_add_u32_e32 v0, 8, v28
	v_and_b32_e32 v0, s33, v0
	v_and_b32_e32 v1, 0xffff0000, v3
	v_lshlrev_b32_e32 v22, 16, v51
	v_cmp_ne_u32_e32 vcc, 0, v0
	v_and_b32_e32 v29, 16, v3
	v_and_b32_e32 v28, 0xffff0000, v2
	v_lshlrev_b32_e32 v31, 16, v3
	v_lshlrev_b32_e32 v3, 16, v2
	v_mov_b32_e32 v2, v23
	v_cndmask_b32_e32 v27, 0, v22, vcc
	v_pk_mov_b32 v[22:23], v[2:3], v[28:29] op_sel:[1,0]
	v_mov_b32_e32 v0, v31
	v_pk_mul_f32 v[22:23], v[4:5], v[22:23] op_sel_hi:[0,1]
	v_mov_b32_e32 v30, v28
	v_pk_fma_f32 v[2:3], v[10:11], v[2:3], v[22:23] op_sel_hi:[0,1,1]
	v_pk_mul_f32 v[22:23], v[4:5], v[0:1] op_sel_hi:[0,1]
	v_pk_fma_f32 v[22:23], v[10:11], v[30:31], v[22:23] op_sel_hi:[0,1,1]
; #define LAS __attribute__((address_space(3)))
; __device__ __forceinline__ unsigned pk2(float lo, float hi) { const f32x2_t f = {lo, hi}; const bf16x2_t b = __builtin_convertvector(f, bf16x2_t); return __builtin_bit_cast(unsigned, b); }
; __device__ __forceinline__ void conv_item(const Params& P, int slice, int item, LAS unsigned char* lds) {
;     ...
; #pragma unroll
;     for (int hh = 0; hh < 2; ++hh) {
;       Sc4Raw zr[4][2];
; #pragma unroll
;       for (int i4 = 0; i4 < 4; ++i4) { const int tok = 8 * (ht + 256 * (4 * hh + i4)); zr[i4][0] = sc4_load(row, tok); zr[i4][1] = sc4_load(row, tok + 4); }
;       __builtin_amdgcn_sched_barrier(0);
; #pragma unroll
;       for (int i4 = 0; i4 < 4; ++i4) {
;         const int tok = 8 * (ht + 256 * (4 * hh + i4));
;         const f32x4 a = sc4_apply(zr[i4][0], tok, L, w0, w1, w2, bb), bq = sc4_apply(zr[i4][1], tok + 4, L, w0, w1, w2, bb);
;         const int Bk = tok >> 7, bs = Bk / nblk;
;         u32x4 o; o.x = pk2(a[0], a[1]); o.y = pk2(a[2], a[3]); o.z = pk2(bq[0], bq[1]); o.w = pk2(bq[2], bq[3]);
;         *(LAS u32x4*)(Zs + Bk * ZBLK + bs * 32 + 2 * (tok & 127)) = o;
	v_mov_b32_e32 v26, v1
	v_lshrrev_b32_e32 v19, 4, v19
	v_pk_add_f32 v[20:21], v[8:9], v[20:21] op_sel_hi:[0,1]
	v_pk_fma_f32 v[2:3], v[6:7], v[30:31], v[2:3] op_sel_hi:[0,1,1]
	v_pk_fma_f32 v[0:1], v[6:7], v[26:27], v[22:23] op_sel_hi:[0,1,1]
	v_lshrrev_b32_e32 v26, s86, v19
	v_pk_add_f32 v[2:3], v[8:9], v[2:3] op_sel_hi:[0,1]
	v_pk_add_f32 v[22:23], v[8:9], v[0:1] op_sel_hi:[0,1]
	v_cvt_pk_bf16_f32 v0, v20, v21
	v_mad_u32_u24 v19, v19, s85, v18
	v_lshlrev_b32_e32 v20, 6, v26
	v_cvt_pk_bf16_f32 v1, v24, v25
	v_cvt_pk_bf16_f32 v2, v2, v3
	v_cvt_pk_bf16_f32 v3, v22, v23
	v_add3_u32 v19, v19, v20, v11
	ds_write_b128 v19, v[0:3]
	s_movk_i32 s9, 0x5000
	v_add_co_u32_e32 v0, vcc, s9, v12
	s_movk_i32 s9, 0x6000
	s_nop 0
	v_addc_co_u32_e32 v1, vcc, 0, v13, vcc
	v_add_co_u32_e32 v2, vcc, s9, v12
	s_movk_i32 s9, 0x7000
	s_nop 0
	v_addc_co_u32_e32 v3, vcc, 0, v13, vcc
	global_load_dwordx4 v[20:23], v[16:17], off
	global_load_ushort v19, v[16:17], off offset:8
	global_load_ushort v34, v[16:17], off offset:16
	global_load_ushort v38, v[16:17], off offset:4094
	global_load_dwordx4 v[24:27], v[2:3], off offset:-4096
	global_load_dwordx4 v[28:31], v[2:3], off
	s_nop 0
	global_load_ushort v14, v[14:15], off offset:4094
	s_nop 0
	global_load_ushort v39, v[0:1], off offset:8
	global_load_ushort v40, v[0:1], off offset:16
	global_load_ushort v41, v[0:1], off offset:4094
	v_add_co_u32_e32 v12, vcc, s9, v12
	v_or_b32_e32 v0, 0x3804, v42
	s_nop 0
	v_addc_co_u32_e32 v13, vcc, 0, v13, vcc
	v_min_u32_e32 v0, 0x3ffb, v0
	global_load_ushort v43, v[2:3], off offset:8
	global_load_ushort v44, v[2:3], off offset:16
	global_load_ushort v45, v[2:3], off offset:4094
	v_lshlrev_b32_e32 v15, 1, v0
	global_load_dwordx4 v[0:3], v[12:13], off
	global_load_ushort v42, v[12:13], off offset:8
	global_load_ushort v46, v15, s[4:5] offset:8
	s_movk_i32 s4, 0x400
	v_or_b32_sdwa v47, v9, s4 dst_sel:DWORD dst_unused:UNUSED_PAD src0_sel:BYTE_0 src1_sel:DWORD
	v_lshlrev_b32_e32 v35, 3, v47
	v_and_b32_e32 v13, s33, v35
	s_waitcnt vmcnt(15)
	v_lshlrev_b32_e32 v12, 16, v20
	s_waitcnt vmcnt(9)
	v_lshlrev_b32_e32 v14, 16, v14
	v_cmp_ne_u32_e32 vcc, 0, v13
	v_and_b32_e32 v20, 0xffff0000, v20
	v_and_b32_e32 v15, 0xffff0000, v21
	v_cndmask_b32_e32 v17, 0, v14, vcc
	v_lshlrev_b32_e32 v21, 16, v21
	v_mov_b32_e32 v16, v20
	v_mov_b32_e32 v14, v21
	v_pk_mul_f32 v[16:17], v[4:5], v[16:17]
	v_lshlrev_b32_e32 v33, 16, v19
	v_pk_fma_f32 v[12:13], v[4:5], v[12:13], v[16:17] op_sel:[0,0,1] op_sel_hi:[1,0,0]
	v_pk_mul_f32 v[16:17], v[4:5], v[14:15] op_sel_hi:[0,1]
	v_add_u32_e32 v14, 8, v35
	v_pk_fma_f32 v[12:13], v[6:7], v[20:21], v[12:13] op_sel_hi:[0,1,1]
	v_pk_fma_f32 v[16:17], v[10:11], v[20:21], v[16:17] op_sel_hi:[0,1,1]
	v_and_b32_e32 v21, 0xffff0000, v23
	v_and_b32_e32 v14, s33, v14
	v_lshlrev_b32_e32 v19, 16, v34
	v_and_b32_e32 v35, 16, v23
	v_and_b32_e32 v34, 0xffff0000, v22
	v_lshlrev_b32_e32 v37, 16, v23
	v_lshlrev_b32_e32 v23, 16, v22
	v_mov_b32_e32 v22, v15
	v_mov_b32_e32 v32, v15
	v_cmp_ne_u32_e32 vcc, 0, v14
	v_pk_mov_b32 v[14:15], v[22:23], v[34:35] op_sel:[1,0]
	v_mov_b32_e32 v20, v37
	v_pk_mul_f32 v[14:15], v[4:5], v[14:15] op_sel_hi:[0,1]
	v_mov_b32_e32 v36, v34
	v_pk_fma_f32 v[14:15], v[10:11], v[22:23], v[14:15] op_sel_hi:[0,1,1]
	v_pk_mul_f32 v[22:23], v[4:5], v[20:21] op_sel_hi:[0,1]
	v_pk_fma_f32 v[16:17], v[6:7], v[32:33], v[16:17] op_sel_hi:[0,1,1]
	v_cndmask_b32_e32 v33, 0, v19, vcc
	v_pk_fma_f32 v[22:23], v[10:11], v[36:37], v[22:23] op_sel_hi:[0,1,1]
	v_mov_b32_e32 v32, v21
	v_lshrrev_b32_e32 v19, 4, v47
	v_pk_add_f32 v[12:13], v[8:9], v[12:13] op_sel_hi:[0,1]
	v_pk_add_f32 v[16:17], v[8:9], v[16:17] op_sel_hi:[0,1]
	v_pk_fma_f32 v[14:15], v[6:7], v[36:37], v[14:15] op_sel_hi:[0,1,1]
	v_pk_fma_f32 v[20:21], v[6:7], v[32:33], v[22:23] op_sel_hi:[0,1,1]
	v_lshrrev_b32_e32 v22, s86, v19
	s_movk_i32 s4, 0x500
	v_pk_add_f32 v[14:15], v[8:9], v[14:15] op_sel_hi:[0,1]
	v_pk_add_f32 v[20:21], v[8:9], v[20:21] op_sel_hi:[0,1]
	v_cvt_pk_bf16_f32 v12, v12, v13
	v_cvt_pk_bf16_f32 v13, v16, v17
	v_mad_u32_u24 v16, v19, s85, v18
	v_lshlrev_b32_e32 v17, 6, v22
	v_or_b32_sdwa v19, v9, s4 dst_sel:DWORD dst_unused:UNUSED_PAD src0_sel:BYTE_0 src1_sel:DWORD
	v_cvt_pk_bf16_f32 v14, v14, v15
	v_cvt_pk_bf16_f32 v15, v20, v21
	v_add3_u32 v16, v16, v17, v11
	v_lshlrev_b32_e32 v32, 3, v19
	ds_write_b128 v16, v[12:15]
	v_and_b32_e32 v13, s33, v32
	v_lshlrev_b32_e32 v14, 16, v38
	v_cmp_ne_u32_e32 vcc, 0, v13
	v_and_b32_e32 v22, 0xffff0000, v24
	v_lshlrev_b32_e32 v23, 16, v25
	v_cndmask_b32_e32 v17, 0, v14, vcc
	v_mov_b32_e32 v16, v22
	v_lshlrev_b32_e32 v12, 16, v24
	v_and_b32_e32 v15, 0xffff0000, v25
	v_mov_b32_e32 v14, v23
	v_pk_mul_f32 v[16:17], v[4:5], v[16:17]
	s_waitcnt vmcnt(8)
	v_lshlrev_b32_e32 v21, 16, v39
	v_pk_fma_f32 v[12:13], v[4:5], v[12:13], v[16:17] op_sel:[0,0,1] op_sel_hi:[1,0,0]
	v_pk_mul_f32 v[16:17], v[4:5], v[14:15] op_sel_hi:[0,1]
	v_add_u32_e32 v14, 8, v32
	v_mov_b32_e32 v20, v15
	v_pk_fma_f32 v[16:17], v[10:11], v[22:23], v[16:17] op_sel_hi:[0,1,1]
	v_and_b32_e32 v14, s33, v14
	v_pk_fma_f32 v[16:17], v[6:7], v[20:21], v[16:17] op_sel_hi:[0,1,1]
	v_and_b32_e32 v21, 0xffff0000, v27
	s_waitcnt vmcnt(7)
; #define LAS __attribute__((address_space(3)))
; __device__ __forceinline__ unsigned pk2(float lo, float hi) { const f32x2_t f = {lo, hi}; const bf16x2_t b = __builtin_convertvector(f, bf16x2_t); return __builtin_bit_cast(unsigned, b); }
; __device__ __forceinline__ void conv_item(const Params& P, int slice, int item, LAS unsigned char* lds) {
;     ...
; #pragma unroll
;     for (int hh = 0; hh < 2; ++hh) {
;       Sc4Raw zr[4][2];
; #pragma unroll
;       for (int i4 = 0; i4 < 4; ++i4) { const int tok = 8 * (ht + 256 * (4 * hh + i4)); zr[i4][0] = sc4_load(row, tok); zr[i4][1] = sc4_load(row, tok + 4); }
;       __builtin_amdgcn_sched_barrier(0);
; #pragma unroll
;       for (int i4 = 0; i4 < 4; ++i4) {
;         const int tok = 8 * (ht + 256 * (4 * hh + i4));
;         const f32x4 a = sc4_apply(zr[i4][0], tok, L, w0, w1, w2, bb), bq = sc4_apply(zr[i4][1], tok + 4, L, w0, w1, w2, bb);
;         const int Bk = tok >> 7, bs = Bk / nblk;
;         u32x4 o; o.x = pk2(a[0], a[1]); o.y = pk2(a[2], a[3]); o.z = pk2(bq[0], bq[1]); o.w = pk2(bq[2], bq[3]);
;         *(LAS u32x4*)(Zs + Bk * ZBLK + bs * 32 + 2 * (tok & 127)) = o;
	v_lshlrev_b32_e32 v20, 16, v40
	v_cmp_ne_u32_e32 vcc, 0, v14
	v_and_b32_e32 v25, 16, v27
	v_and_b32_e32 v24, 0xffff0000, v26
	v_lshlrev_b32_e32 v33, 16, v27
	v_lshlrev_b32_e32 v27, 16, v26
	v_mov_b32_e32 v26, v15
	v_pk_fma_f32 v[12:13], v[6:7], v[22:23], v[12:13] op_sel_hi:[0,1,1]
	v_cndmask_b32_e32 v23, 0, v20, vcc
	v_mov_b32_e32 v20, v33
	v_pk_mov_b32 v[14:15], v[26:27], v[24:25] op_sel:[1,0]
	v_mov_b32_e32 v32, v24
	v_pk_mul_f32 v[14:15], v[4:5], v[14:15] op_sel_hi:[0,1]
	v_pk_mul_f32 v[24:25], v[4:5], v[20:21] op_sel_hi:[0,1]
	v_pk_fma_f32 v[14:15], v[10:11], v[26:27], v[14:15] op_sel_hi:[0,1,1]
	v_pk_fma_f32 v[24:25], v[10:11], v[32:33], v[24:25] op_sel_hi:[0,1,1]
	v_mov_b32_e32 v22, v21
	v_lshrrev_b32_e32 v19, 4, v19
	v_pk_add_f32 v[12:13], v[8:9], v[12:13] op_sel_hi:[0,1]
	v_pk_add_f32 v[16:17], v[8:9], v[16:17] op_sel_hi:[0,1]
	v_pk_fma_f32 v[14:15], v[6:7], v[32:33], v[14:15] op_sel_hi:[0,1,1]
	v_pk_fma_f32 v[20:21], v[6:7], v[22:23], v[24:25] op_sel_hi:[0,1,1]
	v_lshrrev_b32_e32 v22, s86, v19
	s_movk_i32 s4, 0x600
	v_pk_add_f32 v[14:15], v[8:9], v[14:15] op_sel_hi:[0,1]
	v_pk_add_f32 v[20:21], v[8:9], v[20:21] op_sel_hi:[0,1]
	v_cvt_pk_bf16_f32 v12, v12, v13
	v_cvt_pk_bf16_f32 v13, v16, v17
	v_mad_u32_u24 v16, v19, s85, v18
	v_lshlrev_b32_e32 v17, 6, v22
	v_or_b32_sdwa v19, v9, s4 dst_sel:DWORD dst_unused:UNUSED_PAD src0_sel:BYTE_0 src1_sel:DWORD
	v_cvt_pk_bf16_f32 v14, v14, v15
	v_cvt_pk_bf16_f32 v15, v20, v21
	v_add3_u32 v16, v16, v17, v11
	v_lshlrev_b32_e32 v24, 3, v19
	ds_write_b128 v16, v[12:15]
	v_and_b32_e32 v13, s33, v24
	s_waitcnt vmcnt(6)
	v_lshlrev_b32_e32 v14, 16, v41
	v_cmp_ne_u32_e32 vcc, 0, v13
	v_and_b32_e32 v22, 0xffff0000, v28
	v_lshlrev_b32_e32 v23, 16, v29
	v_cndmask_b32_e32 v17, 0, v14, vcc
	v_mov_b32_e32 v16, v22
	v_lshlrev_b32_e32 v12, 16, v28
	v_and_b32_e32 v15, 0xffff0000, v29
	v_mov_b32_e32 v14, v23
	v_pk_mul_f32 v[16:17], v[4:5], v[16:17]
	s_waitcnt vmcnt(5)
	v_lshlrev_b32_e32 v21, 16, v43
	v_pk_fma_f32 v[12:13], v[4:5], v[12:13], v[16:17] op_sel:[0,0,1] op_sel_hi:[1,0,0]
	v_pk_mul_f32 v[16:17], v[4:5], v[14:15] op_sel_hi:[0,1]
	v_add_u32_e32 v14, 8, v24
	v_mov_b32_e32 v20, v15
	v_pk_fma_f32 v[16:17], v[10:11], v[22:23], v[16:17] op_sel_hi:[0,1,1]
	v_and_b32_e32 v14, s33, v14
	v_pk_fma_f32 v[16:17], v[6:7], v[20:21], v[16:17] op_sel_hi:[0,1,1]
	s_waitcnt vmcnt(4)
	v_lshlrev_b32_e32 v20, 16, v44
	v_cmp_ne_u32_e32 vcc, 0, v14
	v_and_b32_e32 v25, 16, v31
	v_and_b32_e32 v24, 0xffff0000, v30
	v_lshlrev_b32_e32 v27, 16, v31
	v_lshlrev_b32_e32 v29, 16, v30
	v_mov_b32_e32 v28, v15
	v_pk_fma_f32 v[12:13], v[6:7], v[22:23], v[12:13] op_sel_hi:[0,1,1]
	v_and_b32_e32 v21, 0xffff0000, v31
	v_cndmask_b32_e32 v23, 0, v20, vcc
	v_mov_b32_e32 v20, v27
	v_pk_mov_b32 v[14:15], v[28:29], v[24:25] op_sel:[1,0]
	v_mov_b32_e32 v26, v24
	v_pk_mul_f32 v[14:15], v[4:5], v[14:15] op_sel_hi:[0,1]
	v_pk_mul_f32 v[24:25], v[4:5], v[20:21] op_sel_hi:[0,1]
	v_pk_fma_f32 v[14:15], v[10:11], v[28:29], v[14:15] op_sel_hi:[0,1,1]
	v_pk_fma_f32 v[24:25], v[10:11], v[26:27], v[24:25] op_sel_hi:[0,1,1]
	v_mov_b32_e32 v22, v21
	v_lshrrev_b32_e32 v19, 4, v19
	v_pk_add_f32 v[12:13], v[8:9], v[12:13] op_sel_hi:[0,1]
	v_pk_add_f32 v[16:17], v[8:9], v[16:17] op_sel_hi:[0,1]
	v_pk_fma_f32 v[14:15], v[6:7], v[26:27], v[14:15] op_sel_hi:[0,1,1]
	v_pk_fma_f32 v[20:21], v[6:7], v[22:23], v[24:25] op_sel_hi:[0,1,1]
	v_lshrrev_b32_e32 v22, s86, v19
	s_movk_i32 s4, 0x700
	v_pk_add_f32 v[14:15], v[8:9], v[14:15] op_sel_hi:[0,1]
	v_pk_add_f32 v[20:21], v[8:9], v[20:21] op_sel_hi:[0,1]
	v_cvt_pk_bf16_f32 v12, v12, v13
	v_cvt_pk_bf16_f32 v13, v16, v17
	v_mad_u32_u24 v16, v19, s85, v18
	v_lshlrev_b32_e32 v17, 6, v22
	v_or_b32_sdwa v19, v9, s4 dst_sel:DWORD dst_unused:UNUSED_PAD src0_sel:BYTE_0 src1_sel:DWORD
	v_cvt_pk_bf16_f32 v14, v14, v15
	v_cvt_pk_bf16_f32 v15, v20, v21
	v_add3_u32 v16, v16, v17, v11
	v_lshlrev_b32_e32 v22, 3, v19
	ds_write_b128 v16, v[12:15]
	v_and_b32_e32 v13, s33, v22
	s_waitcnt vmcnt(2)
	v_lshlrev_b32_e32 v12, 16, v0
	v_lshlrev_b32_e32 v14, 16, v45
	v_cmp_ne_u32_e32 vcc, 0, v13
	v_and_b32_e32 v0, 0xffff0000, v0
	v_and_b32_e32 v15, 0xffff0000, v1
	v_cndmask_b32_e32 v17, 0, v14, vcc
	v_lshlrev_b32_e32 v1, 16, v1
	v_mov_b32_e32 v16, v0
	v_mov_b32_e32 v14, v1
	v_pk_mul_f32 v[16:17], v[4:5], v[16:17]
	s_waitcnt vmcnt(1)
	v_lshlrev_b32_e32 v21, 16, v42
	v_pk_fma_f32 v[12:13], v[4:5], v[12:13], v[16:17] op_sel:[0,0,1] op_sel_hi:[1,0,0]
	v_pk_mul_f32 v[16:17], v[4:5], v[14:15] op_sel_hi:[0,1]
	v_mov_b32_e32 v20, v15
	v_pk_fma_f32 v[12:13], v[6:7], v[0:1], v[12:13] op_sel_hi:[0,1,1]
	v_pk_fma_f32 v[0:1], v[10:11], v[0:1], v[16:17] op_sel_hi:[0,1,1]
	v_pk_fma_f32 v[0:1], v[6:7], v[20:21], v[0:1] op_sel_hi:[0,1,1]
	v_pk_add_f32 v[16:17], v[8:9], v[0:1] op_sel_hi:[0,1]
	v_add_u32_e32 v0, 8, v22
	v_and_b32_e32 v0, s33, v0
	v_and_b32_e32 v1, 0xffff0000, v3
	s_waitcnt vmcnt(0)
; #define LAS __attribute__((address_space(3)))
; #define GAS __attribute__((address_space(1)))
; __device__ __forceinline__ unsigned pk2(float lo, float hi) { const f32x2_t f = {lo, hi}; const bf16x2_t b = __builtin_convertvector(f, bf16x2_t); return __builtin_bit_cast(unsigned, b); }
; __device__ __forceinline__ void conv_item(const Params& P, int slice, int item, LAS unsigned char* lds) {
;     ...
;         const int Bk = tok >> 7, bs = Bk / nblk;
;         u32x4 o; o.x = pk2(a[0], a[1]); o.y = pk2(a[2], a[3]); o.z = pk2(bq[0], bq[1]); o.w = pk2(bq[2], bq[3]);
;         *(LAS u32x4*)(Zs + Bk * ZBLK + bs * 32 + 2 * (tok & 127)) = o;
;     ...
;   const int nsteps = 2 * nblk - 1, dmin = -(nblk - 1);
;   const int aroA = (l16 & 7) * WIN_COPY + 2 * (128 + 8 * kc - 64 * wm - (l16 & 8));
;   const int wdo = (ht >> 5) * WIN_COPY + 4 * (ht & 31);
;   for (int order = 0; order < 2; ++order) {
;     const GAS u16* G = (const GAS u16*)(ws + (L == 2048 ? O_G2K : O_G16K)) + (size_t)(order * 1024 + c) * (size_t)(2 * L);
;     f32x4 acc[4][4];
; #pragma unroll
;     for (int a = 0; a < 4; ++a)
; #pragma unroll
;       for (int b2 = 0; b2 < 4; ++b2) acc[a][b2] = (f32x4){0.f, 0.f, 0.f, 0.f};
;     unsigned wl[8];
;     const int ub = L - 129 + 2 * (ht & 31) - (ht >> 5);
;     ...
;     { unsigned w4[CONV_GRP][8];
; #pragma unroll
;       for (int t0 = 0; t0 < CONV_GRP; ++t0) { CONV_LOADWIN(dmin + t0);
; #pragma unroll
;         for (int q = 0; q < 8; ++q) w4[t0][q] = wl[q]; }
;       __builtin_amdgcn_sched_barrier(0);
; #pragma unroll
;       for (int t0 = 0; t0 < CONV_GRP; ++t0) {
; #pragma unroll
;         for (int q = 0; q < 8; ++q) wl[q] = w4[t0][q];
;         CONV_STOREWIN(t0); }
;     }
;     __syncthreads();
;     const int q0 = 2 * wn, q1 = 2 * wn + 1;
;     const int lo0 = ((32 * q0) >> nbsh) - (nblk - 1), hi0 = (32 * q0 + 31) >> nbsh, lo1 = ((32 * q1) >> nbsh) - (nblk - 1), hi1 = (32 * q1 + 31) >> nbsh;
;     const int n0 = 32 * q0 + l16, n1 = 32 * q1 + l16;
;     const int bk0 = n0 >> nbsh, bs0 = n0 & (nb - 1); (void)n1;
;     const LAS unsigned char* zb0 = Zs + (bs0 * nblk) * ZBLK + bs0 * 32 + 16 * kc;
	v_lshlrev_b32_e32 v5, 16, v46
	v_cmp_ne_u32_e32 vcc, 0, v0
	v_and_b32_e32 v21, 16, v3
	v_and_b32_e32 v20, 0xffff0000, v2
	v_lshlrev_b32_e32 v23, 16, v3
	v_lshlrev_b32_e32 v3, 16, v2
	v_mov_b32_e32 v2, v15
	v_cndmask_b32_e32 v5, 0, v5, vcc
	v_pk_mov_b32 v[14:15], v[2:3], v[20:21] op_sel:[1,0]
	v_mov_b32_e32 v0, v23
	v_pk_mul_f32 v[14:15], v[4:5], v[14:15] op_sel_hi:[0,1]
	v_mov_b32_e32 v22, v20
	v_pk_fma_f32 v[2:3], v[10:11], v[2:3], v[14:15] op_sel_hi:[0,1,1]
	v_pk_mul_f32 v[14:15], v[4:5], v[0:1] op_sel_hi:[0,1]
	v_pk_fma_f32 v[14:15], v[10:11], v[22:23], v[14:15] op_sel_hi:[0,1,1]
	v_mov_b32_e32 v4, v1
	v_pk_fma_f32 v[2:3], v[6:7], v[22:23], v[2:3] op_sel_hi:[0,1,1]
	v_pk_fma_f32 v[0:1], v[6:7], v[4:5], v[14:15] op_sel_hi:[0,1,1]
	v_lshrrev_b32_e32 v6, 4, v19
	v_pk_add_f32 v[12:13], v[8:9], v[12:13] op_sel_hi:[0,1]
	v_pk_add_f32 v[2:3], v[8:9], v[2:3] op_sel_hi:[0,1]
	v_pk_add_f32 v[4:5], v[8:9], v[0:1] op_sel_hi:[0,1]
	v_lshrrev_b32_e32 v8, s86, v6
	v_cvt_pk_bf16_f32 v2, v2, v3
	v_cvt_pk_bf16_f32 v3, v4, v5
	v_mad_u32_u24 v4, v6, s85, v18
	v_lshlrev_b32_e32 v5, 6, v8
	v_cvt_pk_bf16_f32 v0, v12, v13
	v_cvt_pk_bf16_f32 v1, v16, v17
	v_add3_u32 v4, v4, v5, v11
	ds_write_b128 v4, v[0:3]
	v_readlane_b32 s4, v254, 14
	v_and_b32_e32 v4, 31, v9
	s_add_u32 s13, s0, s4
	v_lshlrev_b32_e32 v5, 2, v4
	s_addc_u32 s22, s1, 0
	v_lshlrev_b32_e32 v4, 1, v4
	v_readlane_b32 s4, v254, 15
	s_lshl_b32 s23, s8, 6
	v_bfe_u32 v2, v9, 5, 3
	v_add_u32_e32 v6, s4, v4
	s_or_b32 s4, s23, 31
	s_ashr_i32 s26, s4, s94
	s_or_b32 s4, s23, 32
	s_ashr_i32 s4, s4, s94
	v_and_or_b32 v1, v9, 8, s18
	v_mul_u32_u24_e32 v3, 0x240, v2
	s_ashr_i32 s24, s23, s94
	s_sub_i32 s27, s4, s88
	s_or_b32 s4, s23, 63
	v_and_b32_e32 v0, 7, v9
	v_lshlrev_b32_e32 v1, 1, v1
	v_add3_u32 v157, s3, v3, v5
	s_sub_i32 s25, s24, s88
	s_ashr_i32 s28, s4, s94
	v_and_or_b32 v3, v9, 15, s23
	v_mul_u32_u24_e32 v0, 0x240, v0
	v_sub_u32_e32 v1, v7, v1
	v_ashrrev_i32_e32 v242, s94, v3
	v_and_b32_e32 v3, s56, v9
	s_cmp_lt_i32 s89, s25
	v_lshlrev_b32_e32 v5, s86, v3
	s_cselect_b64 s[4:5], -1, 0
	v_add3_u32 v243, s3, v1, v0
	v_readlane_b32 s3, v254, 30
	s_sub_i32 s64, s26, s30
	s_sub_i32 s92, s28, s30
	v_mad_u32_u24 v8, v5, s85, v18
	v_lshlrev_b32_e32 v3, 6, v3
	s_add_i32 s29, 0, 0x24400
	s_add_i32 s34, s25, s30
	s_add_i32 s35, s27, s30
	v_add_u32_e32 v247, s3, v242
	s_add_i32 s3, s64, 1
	s_add_i32 s84, s26, 1
	s_add_i32 s93, s92, 1
	s_add_i32 s99, s28, 1
	v_sub_u32_e32 v6, v6, v2
	v_add3_u32 v156, v8, v3, v7
	v_readlane_b32 s8, v254, 23
	v_subrev_u32_e32 v9, s25, v242
	v_add_u32_e32 v245, s30, v242
	s_add_u32 s0, s0, s6
	v_add_u32_e32 v8, s8, v6
	v_mad_u64_u32 v[0:1], s[8:9], v9, s85, v[156:157]
	v_mov_b32_e32 v10, s29
	v_cmp_gt_u32_e32 vcc, s61, v9
	v_subrev_u32_e32 v9, s25, v245
	s_addc_u32 s1, s1, s7
	v_cndmask_b32_e32 v244, v10, v0, vcc
	v_mad_u64_u32 v[0:1], s[8:9], v9, s85, v[156:157]
	v_cmp_gt_u32_e32 vcc, s61, v9
	s_add_u32 s14, s0, 0x31912000
	v_readlane_b32 s0, v254, 16
	v_cndmask_b32_e32 v246, v10, v0, vcc
	s_addc_u32 s15, s1, 0
	v_add_u32_e32 v0, s0, v6
	v_mov_b32_e32 v1, s0
	v_cmp_le_u32_e32 vcc, s60, v0
	v_add_u32_e32 v248, s30, v247
	v_mov_b32_e32 v159, v81
	v_addc_co_u32_e32 v9, vcc, v6, v1, vcc
	v_cmp_le_u32_e32 vcc, s33, v0
	v_min_u32_e32 v158, s95, v9
	v_add_u32_e32 v9, 64, v0
	v_addc_co_u32_e64 v10, s[0:1], v6, v1, vcc
	v_add_u32_e32 v10, 1, v10
	v_cmp_le_u32_e64 s[0:1], s60, v9
	v_min_u32_e32 v160, s95, v10
	v_mov_b32_e32 v161, v81
	v_addc_co_u32_e64 v10, s[0:1], 64, v0, s[0:1]
	v_cmp_le_u32_e64 s[0:1], s33, v9
	v_min_u32_e32 v162, s95, v10
	v_mov_b32_e32 v163, v81
	v_addc_co_u32_e64 v9, s[6:7], v6, v1, s[0:1]
	v_add_u32_e32 v9, 0x41, v9
	v_min_u32_e32 v164, s95, v9
	v_add_u32_e32 v9, 0x80, v0
	v_cmp_le_u32_e64 s[6:7], s60, v9
	v_mov_b32_e32 v165, v81
	v_mov_b32_e32 v167, v81
	v_addc_co_u32_e64 v10, s[6:7], v0, v230, s[6:7]
	v_cmp_le_u32_e64 s[6:7], s33, v9
	v_min_u32_e32 v166, s95, v10
	v_mov_b32_e32 v169, v81
	v_addc_co_u32_e64 v9, s[6:7], v6, v1, s[6:7]
	v_add_u32_e32 v9, 0x81, v9
	v_min_u32_e32 v168, s95, v9
	v_add_u32_e32 v9, 0xc0, v0
	v_cmp_le_u32_e64 s[6:7], s60, v9
	v_mov_b32_e32 v171, v81
	v_mov_b32_e32 v173, v81
	v_addc_co_u32_e64 v10, s[6:7], v0, v231, s[6:7]
; #define LAS __attribute__((address_space(3)))
; #define CONV_STOREWIN(t) do { LAS unsigned char* wd_ = Wn + ((((t) >> 2) & 1) * CONV_GRP + ((t) & 3)) * WIN_BYTES + wdo; _Pragma("unroll") for (int q = 0; q < 8; ++q) LAUNDER_V(wl[q]); _Pragma("unroll") for (int q = 0; q < 4; ++q) \
;       *(LAS unsigned*)(wd_ + 128 * q) = wl[2 * q] | (wl[2 * q + 1] << 16); } while (0)
; __device__ __forceinline__ void conv_item(const Params& P, int slice, int item, LAS unsigned char* lds) {
;     ...
;     const int ub = L - 129 + 2 * (ht & 31) - (ht >> 5);
;     ...
;     { unsigned w4[CONV_GRP][8];
; #pragma unroll
;       for (int t0 = 0; t0 < CONV_GRP; ++t0) { CONV_LOADWIN(dmin + t0);
; #pragma unroll
;         for (int q = 0; q < 8; ++q) w4[t0][q] = wl[q]; }
;       __builtin_amdgcn_sched_barrier(0);
; #pragma unroll
;       for (int t0 = 0; t0 < CONV_GRP; ++t0) {
; #pragma unroll
;         for (int q = 0; q < 8; ++q) wl[q] = w4[t0][q];
;         CONV_STOREWIN(t0); }
;     }
;     __syncthreads();
;     const int q0 = 2 * wn, q1 = 2 * wn + 1;
;     const int lo0 = ((32 * q0) >> nbsh) - (nblk - 1), hi0 = (32 * q0 + 31) >> nbsh, lo1 = ((32 * q1) >> nbsh) - (nblk - 1), hi1 = (32 * q1 + 31) >> nbsh;
;     const int n0 = 32 * q0 + l16, n1 = 32 * q1 + l16;
;     const int bk0 = n0 >> nbsh, bs0 = n0 & (nb - 1); (void)n1;
;     const LAS unsigned char* zb0 = Zs + (bs0 * nblk) * ZBLK + bs0 * 32 + 16 * kc;
;     ...
;     bf16x8 fa[10], fb[8];
	v_cmp_le_u32_e64 s[6:7], s33, v9
	v_mov_b32_e32 v9, 0xffffff80
	v_min_u32_e32 v170, s95, v10
	v_addc_co_u32_e64 v1, s[6:7], v6, v1, s[6:7]
	v_add_u32_e32 v1, 0xc1, v1
	v_min_u32_e32 v172, s95, v1
	v_add_u32_e32 v1, 0xffffff80, v0
	v_cmp_le_u32_e64 s[6:7], s60, v1
	v_mov_b32_e32 v175, v81
	v_mov_b32_e32 v177, v81
	v_addc_co_u32_e64 v6, s[6:7], v0, v9, s[6:7]
	v_cmp_le_u32_e64 s[6:7], s33, v1
	v_min_u32_e32 v174, s95, v6
	v_mov_b32_e32 v181, v81
	v_addc_co_u32_e64 v1, s[8:9], v0, v9, s[6:7]
	v_add_u32_e32 v1, 1, v1
	v_min_u32_e32 v176, s95, v1
	v_subrev_u32_e32 v1, 64, v0
	v_cmp_le_u32_e64 s[8:9], s33, v1
	v_mov_b32_e32 v179, v81
	v_mov_b32_e32 v183, v81
	v_addc_co_u32_e64 v6, s[10:11], v0, v9, s[8:9]
	v_cmp_le_u32_e64 s[10:11], s60, v1
	v_not_b32_e32 v1, 63
	v_add_u32_e32 v6, 0x41, v6
	v_addc_co_u32_e64 v1, s[10:11], v0, v1, s[10:11]
	v_min_u32_e32 v180, s95, v1
	v_addc_co_u32_e32 v1, vcc, v0, v9, vcc
	v_add_u32_e32 v1, 0x81, v1
	v_min_u32_e32 v182, s95, v1
	v_addc_co_u32_e64 v1, vcc, v0, v9, s[0:1]
	v_add_u32_e32 v1, 0xc1, v1
	v_min_u32_e32 v184, s95, v1
	v_add_u32_e32 v1, 0xffffff00, v0
	v_cmp_le_u32_e32 vcc, s60, v1
	v_mov_b32_e32 v9, 0xffffff00
	v_min_u32_e32 v178, s95, v6
	v_addc_co_u32_e32 v6, vcc, v0, v9, vcc
	v_cmp_le_u32_e32 vcc, s33, v1
	v_min_u32_e32 v186, s95, v6
	v_mov_b32_e32 v6, 0xffffff40
	v_addc_co_u32_e32 v1, vcc, v0, v9, vcc
	v_add_u32_e32 v1, 1, v1
	v_min_u32_e32 v188, s95, v1
	v_add_u32_e32 v1, 0xffffff40, v0
	v_cmp_le_u32_e32 vcc, s60, v1
	v_readlane_b32 s0, v254, 25
	v_readlane_b32 s1, v254, 28
	v_addc_co_u32_e32 v6, vcc, v0, v6, vcc
	v_cmp_le_u32_e32 vcc, s33, v1
	v_add_u32_e32 v235, s1, v242
	v_readlane_b32 s1, v254, 32
	v_addc_co_u32_e32 v1, vcc, v0, v9, vcc
	v_add_u32_e32 v1, 0x41, v1
	v_min_u32_e32 v192, s95, v1
	v_addc_co_u32_e64 v1, vcc, v0, v9, s[6:7]
	v_addc_co_u32_e64 v0, vcc, v0, v9, s[8:9]
	v_add_u32_e32 v0, 0xc1, v0
	v_min_u32_e32 v196, s95, v0
	v_add_u32_e32 v0, 0xfffffe00, v8
	v_add_u32_e32 v1, 0x81, v1
	v_cmp_le_u32_e32 vcc, s60, v0
	v_min_u32_e32 v194, s95, v1
	v_mov_b32_e32 v185, v81
	v_addc_co_u32_e32 v1, vcc, v8, v234, vcc
	v_cmp_le_u32_e32 vcc, s33, v0
	v_min_u32_e32 v198, s95, v1
	v_mov_b32_e32 v1, 0xfffffe40
	v_addc_co_u32_e32 v0, vcc, v8, v234, vcc
	v_add_u32_e32 v0, 1, v0
	v_min_u32_e32 v200, s95, v0
	v_add_u32_e32 v0, 0xfffffe40, v8
	v_cmp_le_u32_e32 vcc, s60, v0
	v_mov_b32_e32 v187, v81
	v_mov_b32_e32 v189, v81
	v_addc_co_u32_e32 v1, vcc, v8, v1, vcc
	v_cmp_le_u32_e32 vcc, s33, v0
	v_min_u32_e32 v202, s95, v1
	v_mov_b32_e32 v1, 0xfffffe80
	v_addc_co_u32_e32 v0, vcc, v8, v234, vcc
	v_add_u32_e32 v0, 0x41, v0
	v_min_u32_e32 v204, s95, v0
	v_add_u32_e32 v0, 0xfffffe80, v8
	v_cmp_le_u32_e32 vcc, s60, v0
	v_min_u32_e32 v190, s95, v6
	v_mov_b32_e32 v191, v81
	v_addc_co_u32_e32 v1, vcc, v8, v1, vcc
	v_cmp_le_u32_e32 vcc, s33, v0
	v_min_u32_e32 v206, s95, v1
	v_mov_b32_e32 v1, 0xfffffec0
	v_addc_co_u32_e32 v0, vcc, v8, v234, vcc
	v_add_u32_e32 v0, 0x81, v0
	v_min_u32_e32 v208, s95, v0
	v_add_u32_e32 v0, 0xfffffec0, v8
	v_cmp_le_u32_e32 vcc, s60, v0
	v_mov_b32_e32 v193, v81
	v_mov_b32_e32 v195, v81
	v_addc_co_u32_e32 v1, vcc, v8, v1, vcc
	v_cmp_le_u32_e32 vcc, s33, v0
	v_min_u32_e32 v210, s95, v1
	v_mul_lo_u32 v1, v245, s85
	v_addc_co_u32_e32 v0, vcc, v8, v234, vcc
	v_add_u32_e32 v0, 0xc1, v0
	v_min_u32_e32 v212, s95, v0
	v_add_u32_e32 v0, s0, v4
	v_readlane_b32 s0, v254, 26
	v_sub_u32_e32 v249, v0, v2
	v_mov_b32_e32 v197, v81
	v_add_u32_e32 v0, s0, v4
	v_sub_u32_e32 v250, v0, v2
	v_mov_b32_e32 v0, s16
	v_mad_u32_u24 v0, v5, s85, v0
	v_add3_u32 v0, v0, v3, v7
	s_mov_b32 s0, 0xfffffee0
	v_mov_b32_e32 v199, v81
	v_mov_b32_e32 v201, v81
	v_add3_u32 v252, v0, v1, s0
	v_mul_lo_u32 v1, v242, s85
	v_add3_u32 v241, v0, v1, s0
	v_mul_lo_u32 v1, v248, s85
	v_add3_u32 v237, v0, v1, s0
	v_mul_lo_u32 v1, v247, s85
	v_add3_u32 v224, v0, v1, s0
	v_readlane_b32 s0, v254, 34
	v_mov_b32_e32 v203, v81
	v_mov_b32_e32 v205, v81
	v_mov_b32_e32 v207, v81
	v_mov_b32_e32 v209, v81
	v_mov_b32_e32 v211, v81
	v_mov_b32_e32 v213, v81
	v_add_u32_e32 v251, -1, v242
	v_add_u32_e32 v214, 0, v0
	v_add_u32_e32 v236, s1, v242
	v_add_u32_e32 v232, s0, v242
	s_mov_b64 s[0:1], -1
	s_branch .LBB0_387

; #define LAS __attribute__((address_space(3)))
; #define CONV_TAIL() if (step + CONV_GRP < nsteps) CONV_STOREWIN(step + CONV_GRP); if ((step & 1) == 1 || step + 1 == nsteps) __syncthreads()
; #define CONV_DS(x) ({ int t_ = (x); LAUNDER_S(t_); t_; })
; __device__ __forceinline__ void conv_item(const Params& P, int slice, int item, LAS unsigned char* lds) {
;     ...
;     {
;       const LAS unsigned char* wb = CONV_WB(lo0 - dmin); const LAS unsigned char* bp0 = CONV_BPH(0, 0, lo0); const LAS unsigned char* bp1 = CONV_BPH(0, 1, lo0);
; #pragma unroll
;       for (int k = 0; k < 10; ++k) fa[k] = *(const LAS bf16x8*)(wb + 32 * (k - 3));
; #pragma unroll
;       for (int ks = 0; ks < 4; ++ks) { fb[ks] = *(const LAS bf16x8*)(bp0 + 64 * ks); fb[4 + ks] = *(const LAS bf16x8*)(bp1 + 64 * ks); }
;     }
;     const int hw = 16 >> nbsh;
;     ...
;     for (int d = CONV_DS(lo0); d < lo0 + hw; ++d) { CONV_HEADT(); CONV_TILESTEP(0, CONV_BPH(0, 0, d + 1), CONV_BPH(0, 1, d + 1), 1, CONV_WB(step + 1), 1, 1); CONV_TAIL(); }
.LBB0_396:
	ds_read_b128 v[76:79], v243 offset:160
	ds_read_b128 v[88:91], v243 offset:192
	ds_read_b128 v[64:67], v243 offset:224
	ds_read_b128 v[72:75], v243 offset:256
	ds_read_b128 v[60:63], v243 offset:288
	ds_read_b128 v[56:59], v243 offset:320
	ds_read_b128 v[24:27], v243 offset:352
	ds_read_b128 v[28:31], v243 offset:384
	ds_read_b128 v[36:39], v243 offset:416
	ds_read_b128 v[32:35], v243 offset:448
	ds_read_b128 v[144:147], v244
	ds_read_b128 v[140:143], v244 offset:64
	ds_read_b128 v[128:131], v246
	ds_read_b128 v[124:127], v246 offset:64
	ds_read_b128 v[136:139], v244 offset:128
	ds_read_b128 v[132:135], v244 offset:192
	ds_read_b128 v[120:123], v246 offset:128
	ds_read_b128 v[116:119], v246 offset:192
	s_xor_b64 s[10:11], s[0:1], -1
	s_mov_b32 s16, s25
	s_cmp_ge_i32 s16, s34
	s_cbranch_scc1 .LBB0_403
	s_lshl_b32 s0, s16, 7
	v_subrev_u32_e32 v40, s0, v250
	s_mul_i32 s0, s16, 0xfffffee0
	v_mov_b32_e32 v20, 0
	v_subrev_u32_e32 v41, s16, v251
	v_add_u32_e32 v42, s0, v252
	v_add_u32_e32 v43, s0, v241
	v_mov_b32_e32 v21, v20
	v_mov_b32_e32 v22, v20
	v_mov_b32_e32 v23, v20
	v_mov_b32_e32 v16, v20
	v_mov_b32_e32 v17, v20
	v_mov_b32_e32 v18, v20
	v_mov_b32_e32 v19, v20
	v_mov_b32_e32 v12, v20
	v_mov_b32_e32 v13, v20
	v_mov_b32_e32 v14, v20
	v_mov_b32_e32 v15, v20
	v_mov_b32_e32 v8, v20
	v_mov_b32_e32 v9, v20
	v_mov_b32_e32 v10, v20
	v_mov_b32_e32 v11, v20
	s_branch .LBB0_399
.LBB0_398:
	s_add_i32 s16, s16, 1
	v_add_u32_e32 v40, 0xffffff80, v40
	v_add_u32_e32 v41, -1, v41
	v_add_u32_e32 v42, 0xfffffee0, v42
	s_cmp_ge_i32 s16, s34
	v_add_u32_e32 v43, 0xfffffee0, v43
	s_cbranch_scc1 .LBB0_404

; #define CONV_TAIL() if (step + CONV_GRP < nsteps) CONV_STOREWIN(step + CONV_GRP); if ((step & 1) == 1 || step + 1 == nsteps) __syncthreads()
; #define CONV_DS(x) ({ int t_ = (x); LAUNDER_S(t_); t_; })
; __device__ __forceinline__ void conv_item(const Params& P, int slice, int item, LAS unsigned char* lds) {
;     ...
;     for (int d = CONV_DS(lo0); d < lo0 + hw; ++d) { CONV_HEADT(); CONV_TILESTEP(0, CONV_BPH(0, 0, d + 1), CONV_BPH(0, 1, d + 1), 1, CONV_WB(step + 1), 1, 1); CONV_TAIL(); }
;     for (int d = CONV_DS(lo0 + hw); d < lo1; ++d) { CONV_HEADT(); CONV_TILESTEP(0, CONV_BPH(0, 0, d + 1), CONV_BPH(0, 1, d + 1), 1, CONV_WB(step + 1), 3, 1); CONV_TAIL(); }
.LBB0_404:
	s_mov_b32 s16, s34
	s_cmp_ge_i32 s16, s27
	s_cbranch_scc1 .LBB0_411
	s_lshl_b32 s0, s16, 7
	v_subrev_u32_e32 v68, s0, v250
	s_mul_i32 s0, s16, 0xfffffee0
	v_mov_b32_e32 v48, 0
	v_subrev_u32_e32 v69, s16, v251
	v_add_u32_e32 v70, s0, v252
	v_add_u32_e32 v71, s0, v241
	v_mov_b32_e32 v49, v48
	v_mov_b32_e32 v50, v48
	v_mov_b32_e32 v51, v48
	v_mov_b32_e32 v52, v48
	v_mov_b32_e32 v53, v48
	v_mov_b32_e32 v54, v48
	v_mov_b32_e32 v55, v48
	v_mov_b32_e32 v44, v48
	v_mov_b32_e32 v45, v48
	v_mov_b32_e32 v46, v48
	v_mov_b32_e32 v47, v48
	v_mov_b32_e32 v40, v48
	v_mov_b32_e32 v41, v48
	v_mov_b32_e32 v42, v48
	v_mov_b32_e32 v43, v48
	s_branch .LBB0_407
.LBB0_406:
	s_add_i32 s16, s16, 1
	v_add_u32_e32 v68, 0xffffff80, v68
	v_add_u32_e32 v69, -1, v69
	v_add_u32_e32 v70, 0xfffffee0, v70
	s_cmp_ge_i32 s16, s27
	v_add_u32_e32 v71, 0xfffffee0, v71
	s_cbranch_scc1 .LBB0_412

; #define CONV_TAIL() if (step + CONV_GRP < nsteps) CONV_STOREWIN(step + CONV_GRP); if ((step & 1) == 1 || step + 1 == nsteps) __syncthreads()
; #define CONV_DS(x) ({ int t_ = (x); LAUNDER_S(t_); t_; })
; #define CONV_NB1(H) ((d + 1 <= hi0) ? CONV_BPH(0, H, d + 1) : CONV_BPH(1, H, d + 1))
; __device__ __forceinline__ void conv_item(const Params& P, int slice, int item, LAS unsigned char* lds) {
;     ...
;     for (int d = CONV_DS(lo1); d < lo1 + hw; ++d) { CONV_HEADT(); CONV_TILESTEP(0, CONV_BPH(1, 0, d), CONV_BPH(1, 1, d), 0, Wn, 3, 1);
;       CONV_TILESTEP(1, CONV_NB1(0), CONV_NB1(1), 1, CONV_WB(step + 1), 1, 0); CONV_TAIL(); }
.LBB0_414:
	s_add_i32 s16, s16, 1
	s_add_i32 s17, s17, -1
	v_add_u32_e32 v100, 0xffffff80, v100
	s_cmp_ge_i32 s16, s35
	v_add_u32_e32 v82, 0xfffffee0, v82
	s_cbranch_scc1 .LBB0_420

; #define CONV_TAIL() if (step + CONV_GRP < nsteps) CONV_STOREWIN(step + CONV_GRP); if ((step & 1) == 1 || step + 1 == nsteps) __syncthreads()
; #define CONV_DS(x) ({ int t_ = (x); LAUNDER_S(t_); t_; })
; #define CONV_NB1(H) ((d + 1 <= hi0) ? CONV_BPH(0, H, d + 1) : CONV_BPH(1, H, d + 1))
; __device__ __forceinline__ void conv_item(const Params& P, int slice, int item, LAS unsigned char* lds) {
;     ...
;     for (int d = CONV_DS(lo1 + hw); d <= hi0 - hw; ++d) { CONV_HEADT(); CONV_TILESTEP(0, CONV_BPH(1, 0, d), CONV_BPH(1, 1, d), 0, Wn, 3, 1);
;       CONV_TILESTEP(1, CONV_NB1(0), CONV_NB1(1), 1, CONV_WB(step + 1), 3, 0); CONV_TAIL(); }
.LBB0_426:
	s_add_i32 s16, s16, -1
	v_add_u32_e32 v150, 0xffffff80, v150
	v_add_u32_e32 v82, 0xfffffee0, v82
	s_cmp_ge_i32 s68, s64
	v_add_u32_e32 v148, 0xfffffee0, v148
	s_cbranch_scc1 .LBB0_429
	s_mov_b32 s17, s68
	s_branch .LBB0_422

; #define CONV_TAIL() if (step + CONV_GRP < nsteps) CONV_STOREWIN(step + CONV_GRP); if ((step & 1) == 1 || step + 1 == nsteps) __syncthreads()
; #define CONV_DS(x) ({ int t_ = (x); LAUNDER_S(t_); t_; })
; #define CONV_NB1(H) ((d + 1 <= hi0) ? CONV_BPH(0, H, d + 1) : CONV_BPH(1, H, d + 1))
; __device__ __forceinline__ void conv_item(const Params& P, int slice, int item, LAS unsigned char* lds) {
;     ...
;     for (int d = CONV_DS(hi0 - hw + 1); d <= hi0; ++d) { CONV_HEADT(); CONV_TILESTEP(0, CONV_BPH(1, 0, d), CONV_BPH(1, 1, d), 0, Wn, 2, 1);
;       CONV_TILESTEP(1, CONV_NB1(0), CONV_NB1(1), 1, CONV_WB(step + 1), 3, 0); CONV_TAIL(); }
.LBB0_431:
	s_add_i32 s68, s68, 1
	s_add_i32 s69, s69, -1
	v_add_u32_e32 v233, 0xffffff80, v233
	v_add_u32_e32 v82, 0xfffffee0, v82
	v_add_u32_e32 v216, 0xfffffee0, v216
	s_and_b64 vcc, exec, s[16:17]
	s_cbranch_vccnz .LBB0_436

; #define CONV_TAIL() if (step + CONV_GRP < nsteps) CONV_STOREWIN(step + CONV_GRP); if ((step & 1) == 1 || step + 1 == nsteps) __syncthreads()
; #define CONV_DS(x) ({ int t_ = (x); LAUNDER_S(t_); t_; })
; #define CONV_NB1(H) ((d + 1 <= hi0) ? CONV_BPH(0, H, d + 1) : CONV_BPH(1, H, d + 1))
; __device__ __forceinline__ void conv_item(const Params& P, int slice, int item, LAS unsigned char* lds) {
;     ...
;       CONV_TILESTEP(1, CONV_NB1(0), CONV_NB1(1), 1, CONV_WB(step + 1), 3, 0); CONV_TAIL(); }
;     for (int d = CONV_DS(hi0 + 1); d <= hi1 - hw; ++d) { CONV_HEADT(); CONV_TILESTEP(1, CONV_BPH(1, 0, d + 1), CONV_BPH(1, 1, d + 1), 1, CONV_WB(step + 1), 3, 1); CONV_TAIL(); }
.LBB0_436:
	s_mov_b32 s0, s84
	s_cmp_gt_i32 s0, s92
	s_cbranch_scc1 .LBB0_443
	s_add_i32 s16, s0, -1
	s_lshl_b32 s1, s0, 7
	v_subrev_u32_e32 v83, s0, v236
	s_mulk_i32 s0, 0xfee0
	v_subrev_u32_e32 v82, s1, v250
	v_add_u32_e32 v148, s0, v237
	v_add_u32_e32 v149, s0, v224
	s_branch .LBB0_439
.LBB0_438:
	s_add_i32 s16, s16, 1
	v_add_u32_e32 v82, 0xffffff80, v82
	v_add_u32_e32 v83, -1, v83
	v_add_u32_e32 v148, 0xfffffee0, v148
	s_cmp_ge_i32 s16, s92
	v_add_u32_e32 v149, 0xfffffee0, v149
	s_cbranch_scc1 .LBB0_443

; #define CONV_TAIL() if (step + CONV_GRP < nsteps) CONV_STOREWIN(step + CONV_GRP); if ((step & 1) == 1 || step + 1 == nsteps) __syncthreads()
; #define CONV_DS(x) ({ int t_ = (x); LAUNDER_S(t_); t_; })
; __device__ __forceinline__ void conv_item(const Params& P, int slice, int item, LAS unsigned char* lds) {
;     ...
;     for (int d = CONV_DS(hi0 + 1); d <= hi1 - hw; ++d) { CONV_HEADT(); CONV_TILESTEP(1, CONV_BPH(1, 0, d + 1), CONV_BPH(1, 1, d + 1), 1, CONV_WB(step + 1), 3, 1); CONV_TAIL(); }
;     for (int d = CONV_DS(hi1 - hw + 1); d <= hi1; ++d) { CONV_HEADT(); CONV_TILESTEP(1, CONV_BPH(1, 0, d + 1), CONV_BPH(1, 1, d + 1), 1, CONV_WB(step + 1), 2, 1); CONV_TAIL(); }
.LBB0_443:
	s_mov_b32 s0, s93
	s_cmp_gt_i32 s0, s28
	s_cbranch_scc1 .LBB0_450
	s_add_i32 s16, s0, -1
	s_lshl_b32 s1, s0, 7
	v_subrev_u32_e32 v83, s0, v232
	s_mulk_i32 s0, 0xfee0
	v_subrev_u32_e32 v82, s1, v250
	s_waitcnt lgkmcnt(2)
	v_add_u32_e32 v132, s0, v237
	s_branch .LBB0_446
.LBB0_445:
	s_add_i32 s16, s16, 1
	v_add_u32_e32 v82, 0xffffff80, v82
	v_add_u32_e32 v83, -1, v83
	s_cmp_ge_i32 s16, s28
	v_add_u32_e32 v132, 0xfffffee0, v132
	s_cbranch_scc1 .LBB0_450

; #define LAS __attribute__((address_space(3)))
; #define GAS __attribute__((address_space(1)))
; #define LAUNDER_V(x) asm volatile("" : "+v"(x))
; __device__ __forceinline__ unsigned pk2(float lo, float hi) { const f32x2_t f = {lo, hi}; const bf16x2_t b = __builtin_convertvector(f, bf16x2_t); return __builtin_bit_cast(unsigned, b); }
; __device__ __forceinline__ float lo16(unsigned v) { return __uint_as_float(v << 16); }
; __device__ __forceinline__ float hi16(unsigned v) { return __uint_as_float(v & 0xffff0000u); }
; __device__ __forceinline__ void conv_item(const Params& P, int slice, int item, LAS unsigned char* lds) {
;     ...
;     {
;       const int gc = 1024 * (order + 1) + c; const u16* grow = hyT + (size_t)gc * TS;
;       const float w0 = wsh[gc], w1 = wsh[3072 + gc], w2 = wsh[6144 + gc], bb = bsh[gc], skip = P.in[I_FSK][order * 1024 + c];
;       GAS u16* zt = (GAS u16*)(ws + O_ZT) + (size_t)c * TS;
;       int te = threadIdx.x; LAUNDER_V(te); const int l16 = te & 15, kc = (te >> 4) & 3;
; #pragma unroll
;       for (int nt = 0; nt < 2; ++nt) {
;         Sc4Raw gr[2][4];
; #pragma unroll
;         for (int hh = 0; hh < 2; ++hh) {
;           const int n = 32 * (2 * wn + nt) + 16 * hh + l16, bk = n >> nbsh, bs = n & (nb - 1), Bo = bs * nblk + bk;
; #pragma unroll
;           for (int mt = 0; mt < 4; ++mt) gr[hh][mt] = sc4_load(grow, Bo * 128 + 64 * wm + 16 * mt + 4 * kc);
;         }
;         __builtin_amdgcn_sched_barrier(0);
; #pragma unroll
;         for (int hh = 0; hh < 2; ++hh) {
;           const int n = 32 * (2 * wn + nt) + 16 * hh + l16, bk = n >> nbsh, bs = n & (nb - 1), Bo = bs * nblk + bk;
; #pragma unroll
;           for (int mt = 0; mt < 4; ++mt) {
;             const int s0 = 64 * wm + 16 * mt + 4 * kc, tok = Bo * 128 + s0;
;             LAS u32x2* zp = (LAS u32x2*)(Zs + Bo * ZBLK + bs * 32 + 2 * s0);
;             const u32x2 zv = *zp; const f32x4 gt = sc4_apply(gr[hh][mt], tok, L, w0, w1, w2, bb);
;             const f32x4 av = acc[mt][2 * nt + hh];
;             const float y0 = gt[0] * (av[0] + skip * lo16(zv.x)), y1 = gt[1] * (av[1] + skip * hi16(zv.x));
;             const float y2 = gt[2] * (av[2] + skip * lo16(zv.y)), y3 = gt[3] * (av[3] + skip * hi16(zv.y));
;             u32x2 o; o.x = pk2(y0, y1); o.y = pk2(y2, y3);
;             if (order == 0) *zp = o; else *(GAS u32x2*)(zt + (unsigned)tok) = o;
.LBB0_459:
	s_add_i32 s8, s6, 0x400
	s_ashr_i32 s9, s8, 31
	s_lshl_b64 s[0:1], s[8:9], 15
	s_add_u32 s0, s19, s0
	s_addc_u32 s1, s20, s1
	s_lshl_b64 s[8:9], s[8:9], 2
	s_add_u32 s16, s52, s8
	s_addc_u32 s17, s53, s9
	s_add_u32 s8, s54, s8
	v_readlane_b32 s68, v253, 56
	s_addc_u32 s9, s55, s9
	s_lshl_b64 s[6:7], s[6:7], 2
	v_readlane_b32 s72, v253, 60
	v_readlane_b32 s73, v253, 61
	s_add_u32 s6, s72, s6
	s_addc_u32 s7, s73, s7
	s_waitcnt vmcnt(4)
	v_mov_b32_e32 v1, v215
	global_load_dword v7, v81, s[16:17]
	global_load_dword v6, v220, s[16:17]
	global_load_dword v0, v221, s[16:17]
	global_load_dword v2, v81, s[8:9]
	global_load_dword v4, v81, s[6:7]
	s_waitcnt lgkmcnt(2)
	v_mov_b32_e32 v29, v81
	s_waitcnt vmcnt(6)
	v_and_b32_e32 v3, s56, v1
	s_waitcnt lgkmcnt(1)
	v_and_or_b32 v63, v1, 15, s23
	v_lshlrev_b32_e32 v62, s86, v3
	s_waitcnt vmcnt(5)
	v_lshrrev_b32_e32 v5, 2, v1
	v_ashrrev_i32_e32 v1, s94, v63
	v_add_u32_e32 v1, v1, v62
	v_and_or_b32 v25, v5, 12, s18
	s_waitcnt lgkmcnt(0)
	v_lshlrev_b32_e32 v72, 7, v1
	v_or_b32_e32 v80, v25, v72
	v_min_i32_e32 v24, 0x3ffb, v80
	v_add_u32_e32 v28, 4, v24
	v_lshl_add_u64 v[28:29], v[28:29], 1, s[0:1]
	v_or_b32_e32 v24, 16, v80
	global_load_ushort v91, v[28:29], off
	v_max_i32_e32 v29, 1, v24
	v_min_i32_e32 v24, 0x3ffb, v24
	v_add_u32_e32 v28, 4, v24
	v_lshlrev_b32_e32 v24, 1, v29
	v_mov_b32_e32 v29, v81
	global_load_ushort v89, v24, s[0:1] offset:-2
	v_lshl_add_u64 v[28:29], v[28:29], 1, s[0:1]
	v_or_b32_e32 v24, 32, v80
	global_load_ushort v90, v[28:29], off
	v_max_i32_e32 v29, 1, v24
	v_min_i32_e32 v24, 0x3ffb, v24
	v_add_u32_e32 v28, 4, v24
	v_lshlrev_b32_e32 v24, 1, v29
	v_lshl_add_u64 v[26:27], v[80:81], 1, s[0:1]
	global_load_ushort v83, v24, s[0:1] offset:-2
	v_or_b32_e32 v24, 48, v80
	global_load_dwordx2 v[60:61], v[26:27], off
	global_load_dwordx2 v[56:57], v[26:27], off offset:32
	global_load_dwordx2 v[38:39], v[26:27], off offset:64
	global_load_dwordx2 v[36:37], v[26:27], off offset:96
	v_max_i32_e32 v27, 1, v24
	v_min_i32_e32 v24, 0x3ffb, v24
	v_add_u32_e32 v26, 4, v24
	v_lshlrev_b32_e32 v24, 1, v27
	global_load_ushort v79, v24, s[0:1] offset:-2
	v_or_b32_e32 v24, 16, v63
	v_ashrrev_i32_e32 v24, s94, v24
	v_add_u32_e32 v76, v24, v62
	v_mov_b32_e32 v29, v81
	v_lshlrev_b32_e32 v64, 7, v76
	v_lshl_add_u64 v[28:29], v[28:29], 1, s[0:1]
	v_or_b32_e32 v32, v25, v64
	global_load_ushort v88, v[28:29], off
	v_max_i32_e32 v24, 1, v32
	v_min_i32_e32 v28, 0x3ffb, v32
	v_add_u32_e32 v28, 4, v28
	v_lshlrev_b32_e32 v24, 1, v24
	v_mov_b32_e32 v29, v81
	global_load_ushort v77, v24, s[0:1] offset:-2
	v_lshl_add_u64 v[28:29], v[28:29], 1, s[0:1]
	v_or_b32_e32 v24, 16, v32
	global_load_ushort v78, v[28:29], off
	v_max_i32_e32 v29, 1, v24
	v_min_i32_e32 v24, 0x3ffb, v24
	v_add_u32_e32 v28, 4, v24
	v_lshlrev_b32_e32 v24, 1, v29
	global_load_ushort v74, v24, s[0:1] offset:-2
	v_or_b32_e32 v24, 32, v32
	v_max_i32_e32 v59, 1, v24
	v_min_i32_e32 v24, 0x3ffb, v24
	v_add_u32_e32 v58, 4, v24
	v_lshlrev_b32_e32 v24, 1, v59
	v_mov_b32_e32 v59, v81
	global_load_ushort v67, v24, s[0:1] offset:-2
	v_lshl_add_u64 v[58:59], v[58:59], 1, s[0:1]
	v_or_b32_e32 v24, 48, v32
	v_mov_b32_e32 v27, v81
	global_load_ushort v73, v[58:59], off
	v_max_i32_e32 v59, 1, v24
	v_min_i32_e32 v24, 0x3ffb, v24
	v_lshl_add_u64 v[26:27], v[26:27], 1, s[0:1]
	v_mov_b32_e32 v33, v81
	v_mov_b32_e32 v29, v81
	v_add_u32_e32 v58, 4, v24
	v_lshlrev_b32_e32 v24, 1, v59
	v_mov_b32_e32 v59, v81
	v_max_i32_e32 v5, 1, v80
	global_load_ushort v82, v[26:27], off
	v_lshl_add_u64 v[26:27], v[32:33], 1, s[0:1]
	v_lshl_add_u64 v[28:29], v[28:29], 1, s[0:1]
	v_lshl_add_u64 v[58:59], v[58:59], 1, s[0:1]
	v_lshlrev_b32_e32 v5, 1, v5
	global_load_dwordx2 v[34:35], v[26:27], off
	global_load_dwordx2 v[30:31], v[26:27], off offset:32
	global_load_ushort v75, v[28:29], off
	global_load_ushort v65, v24, s[0:1] offset:-2
	global_load_ushort v66, v[58:59], off
	v_lshl_add_u32 v24, v3, 6, s21
	global_load_dwordx2 v[28:29], v[26:27], off offset:64
	v_readlane_b32 s69, v253, 57
	global_load_dwordx2 v[26:27], v[26:27], off offset:96
	v_readlane_b32 s70, v253, 58
	global_load_ushort v5, v5, s[0:1] offset:-2
	v_readlane_b32 s71, v253, 59
	v_readlane_b32 s74, v253, 62
	v_readlane_b32 s75, v253, 63
	v_readlane_b32 s76, v254, 0
	v_readlane_b32 s77, v254, 1
	v_readlane_b32 s78, v254, 2
	v_readlane_b32 s79, v254, 3
	v_readlane_b32 s80, v254, 4
	v_readlane_b32 s81, v254, 5
	v_readlane_b32 s82, v254, 6
	v_readlane_b32 s83, v254, 7
	v_mad_u64_u32 v[58:59], s[6:7], v1, s85, v[24:25]
	v_lshlrev_b32_e32 v59, 1, v25
	v_add_u32_e32 v1, v58, v59
	s_waitcnt vmcnt(19)
	v_and_b32_e32 v121, 0xffff0000, v61
	v_bitop3_b32 v3, v25, s33, v72 bitop3:0xc8
	v_lshlrev_b32_e32 v61, 16, v61
	ds_read_b64 v[116:117], v1
	s_waitcnt vmcnt(0)
	v_lshlrev_b32_e32 v5, 16, v5
	v_cmp_ne_u32_e32 vcc, 0, v3
	v_mov_b32_e32 v120, v61
	v_lshlrev_b32_e32 v118, 16, v60
	v_cndmask_b32_e32 v123, 0, v5, vcc
	v_add_u32_e32 v3, 4, v80
	v_and_b32_e32 v60, 0xffff0000, v60
	v_mov_b32_e32 v122, v7
	v_pk_mul_f32 v[126:127], v[6:7], v[120:121] op_sel_hi:[0,1]
	v_and_b32_e32 v3, s33, v3
	v_pk_fma_f32 v[126:127], v[122:123], v[60:61], v[126:127] op_sel_hi:[0,1,1]
	v_mov_b32_e32 v122, v60
	v_lshlrev_b32_e32 v5, 16, v91
	v_cmp_ne_u32_e32 vcc, 0, v3
	v_pk_mul_f32 v[122:123], v[6:7], v[122:123]
	v_mov_b32_e32 v124, v121
	v_cndmask_b32_e32 v125, 0, v5, vcc
	v_pk_fma_f32 v[118:119], v[6:7], v[118:119], v[122:123] op_sel:[0,0,1] op_sel_hi:[1,0,0]
	v_pk_fma_f32 v[120:121], v[0:1], v[124:125], v[126:127] op_sel_hi:[0,1,1]
	s_waitcnt lgkmcnt(0)
	v_lshlrev_b32_e32 v124, 16, v116
	v_and_b32_e32 v125, 0xffff0000, v116
	v_pk_fma_f32 v[60:61], v[0:1], v[60:61], v[118:119] op_sel_hi:[0,1,1]
	v_pk_fma_f32 v[16:17], v[4:5], v[124:125], v[16:17] op_sel_hi:[0,1,1]
	v_pk_add_f32 v[60:61], v[2:3], v[60:61] op_sel_hi:[0,1]
	v_pk_mul_f32 v[16:17], v[60:61], v[16:17]
	v_lshlrev_b32_e32 v60, 16, v117
	v_and_b32_e32 v61, 0xffff0000, v117
	v_pk_add_f32 v[120:121], v[2:3], v[120:121] op_sel_hi:[0,1]
	v_pk_fma_f32 v[18:19], v[4:5], v[60:61], v[18:19] op_sel_hi:[0,1,1]
	v_pk_mul_f32 v[18:19], v[120:121], v[18:19]
	v_cvt_pk_bf16_f32 v16, v16, v17
	v_cvt_pk_bf16_f32 v17, v18, v19
	s_mov_b64 s[6:7], -1
	s_and_b64 vcc, exec, s[10:11]
	s_cbranch_vccz .LBB0_461
	v_lshl_add_u64 v[18:19], v[80:81], 1, s[14:15]
	global_store_dwordx2 v[18:19], v[16:17], off
	s_mov_b64 s[6:7], 0

; __global__ void __launch_bounds__(512) fwd_megakernel(Params P) {
;     ...
;         const int NATT = 768, NCONV = 512;
;         for (int it = blockIdx.x; it < NATT + NCONV; it += gridDim.x) { if (it < NATT) attn_item(P, s, it, lds); else conv_item(P, s, it - NATT, lds); }
.LBB0_523:
	s_movk_i32 s85, 0x110
	s_and_b64 vcc, exec, s[0:1]
	s_cbranch_vccz .LBB0_381
	v_readlane_b32 s4, v253, 0
	v_readlane_b32 s5, v253, 1
	v_readlane_b32 s6, v253, 2
	v_readlane_b32 s7, v253, 3
	s_mov_b64 s[4:5], s[6:7]
	v_mov_b32_e32 v107, v215
	v_readlane_b32 s0, v253, 23
	v_readlane_b32 s1, v253, 24
	v_and_b32_e32 v77, 15, v107
	v_readfirstlane_b32 s72, v107
	s_andn2_b64 vcc, exec, s[0:1]
	v_lshlrev_b32_e32 v8, 3, v77
	s_cbranch_vccnz .LBB0_526
	v_lshlrev_b32_e32 v4, 2, v8
	global_load_dwordx4 v[0:3], v4, s[48:49] offset:16
	s_nop 0
	global_load_dwordx4 v[4:7], v4, s[48:49]
	s_branch .LBB0_527

; __global__ void __launch_bounds__(512) fwd_megakernel(Params P) {
;     ...
;     if (ph + 1 < P.ph_hi) {
;       asm volatile("s_waitcnt vmcnt(0) lgkmcnt(0)" ::: "memory");
;       __syncthreads();
;       if (ph == P.ph_lo) {
;         if (threadIdx.x < 64) { __builtin_amdgcn_fence(__ATOMIC_RELEASE, "agent"); asm volatile("s_waitcnt vmcnt(0)" ::: "memory"); }
;         __syncthreads();
;         grid.sync();
;         __builtin_amdgcn_fence(__ATOMIC_ACQUIRE, "agent");
;         asm volatile("s_waitcnt vmcnt(0)" ::: "memory");
;       } else {
;         if (threadIdx.x == 0) {
;           unsigned* ctr = (unsigned*)(ws + O_CTR);
;           const unsigned target = (unsigned)(ph - P.ph_lo) * gridDim.x;
;           __builtin_amdgcn_fence(__ATOMIC_RELEASE, "agent");
;           asm volatile("s_waitcnt vmcnt(0)" ::: "memory");
;           __hip_atomic_fetch_add(ctr, 1u, __ATOMIC_RELAXED, __HIP_MEMORY_SCOPE_AGENT);
;           while (__hip_atomic_load(ctr, __ATOMIC_RELAXED, __HIP_MEMORY_SCOPE_AGENT) < target) __builtin_amdgcn_s_sleep(2);
;           __builtin_amdgcn_fence(__ATOMIC_ACQUIRE, "agent");
;           asm volatile("s_waitcnt vmcnt(0)" ::: "memory");
;         }
;         __syncthreads();
;       }
.LBB0_967:
	v_readlane_b32 s3, v255, 60
	s_mov_b64 s[0:1], -1
	s_cmp_ge_u32 s3, 28
	s_cbranch_scc1 .LBB0_7
	s_add_i32 s4, s3, 1
	v_writelane_b32 v255, s4, 60
	s_mov_b32 s5, 0
	s_mov_b32 s6, 0
	s_mov_b32 s2, s4
	s_cmp_lt_u32 s4, 3
	s_cbranch_scc1 .Lsch_have
	s_add_i32 s2, s4, -4
	s_cmp_gt_u32 s4, 18
	s_cbranch_scc1 .Lsch_have
	s_add_i32 s7, s4, -3
	s_lshr_b32 s8, s7, 2
	s_and_b32 s7, s7, 3
	s_mul_i32 s8, s8, 3
	s_add_i32 s9, s7, 1
	s_lshr_b32 s9, s9, 1
	s_add_i32 s2, s8, s9
	s_add_i32 s2, s2, 3
	s_cmp_eq_u32 s7, 1
	s_cselect_b32 s5, 2, 0
	s_cmp_eq_u32 s7, 2
	s_cselect_b32 s6, 1, 0
.Lsch_have:
	v_writelane_b32 v255, s5, 57
	v_writelane_b32 v255, s6, 58
	s_cmp_lt_u32 s3, 3
	s_cbranch_scc1 .Lsch_bar
	s_cmp_gt_u32 s3, 18
	s_cbranch_scc1 .Lsch_bar
	s_add_i32 s7, s3, -3
	s_bitcmp1_b32 s7, 0
	s_cbranch_scc1 .Lsch_bar
	s_waitcnt vmcnt(0) lgkmcnt(0)
	s_barrier
	s_branch .LBB0_8
.Lsch_bar:
	s_waitcnt vmcnt(0) lgkmcnt(0)
	v_readlane_b32 s0, v253, 4
	v_readlane_b32 s1, v253, 5
	s_cmp_lg_u32 s72, s0
	s_mov_b64 s[0:1], -1
	s_waitcnt vmcnt(0) lgkmcnt(0)
	s_barrier
	s_cbranch_scc0 .LBB0_975
	s_mov_b64 s[0:1], exec
	v_readlane_b32 s4, v253, 50
	v_readlane_b32 s5, v253, 51
	s_and_b64 s[4:5], s[0:1], s[4:5]
	s_mov_b64 exec, s[4:5]
	s_cbranch_execz .LBB0_974
	v_readlane_b32 s4, v254, 10
	v_readlane_b32 s5, v254, 11
	buffer_wbl2 sc1
	v_mov_b32_e32 v0, s4
	v_add_co_u32_e32 v0, vcc, 0x3f912000, v0
	v_mov_b32_e32 v1, s5
	s_waitcnt vmcnt(0)
	s_nop 0
	v_addc_co_u32_e32 v1, vcc, 0, v1, vcc
	v_mov_b32_e32 v2, 1
	flat_atomic_add v[0:1], v2
	flat_load_dword v0, v[0:1] sc1
	s_add_u32 s4, s4, 0x3f912000
	v_readlane_b32 s6, v253, 4
	s_addc_u32 s5, s5, 0
	v_readlane_b32 s3, v255, 59
	v_readlane_b32 s6, v253, 6
	s_mul_i32 s3, s3, s6
	v_readlane_b32 s7, v253, 5
	s_waitcnt vmcnt(0) lgkmcnt(0)
	v_cmp_gt_u32_e32 vcc, s3, v0
	s_and_saveexec_b64 s[6:7], vcc
	s_cbranch_execz .LBB0_973
	s_mov_b64 s[8:9], 0

; __global__ void __launch_bounds__(512) fwd_megakernel(Params P) {
;     ...
;         if (threadIdx.x == 0) {
;           unsigned* ctr = (unsigned*)(ws + O_CTR);
;           const unsigned target = (unsigned)(ph - P.ph_lo) * gridDim.x;
;           __builtin_amdgcn_fence(__ATOMIC_RELEASE, "agent");
;           asm volatile("s_waitcnt vmcnt(0)" ::: "memory");
;           __hip_atomic_fetch_add(ctr, 1u, __ATOMIC_RELAXED, __HIP_MEMORY_SCOPE_AGENT);
;           while (__hip_atomic_load(ctr, __ATOMIC_RELAXED, __HIP_MEMORY_SCOPE_AGENT) < target) __builtin_amdgcn_s_sleep(2);
;           __builtin_amdgcn_fence(__ATOMIC_ACQUIRE, "agent");
;           asm volatile("s_waitcnt vmcnt(0)" ::: "memory");
;         }
;         __syncthreads();
;       }
.LBB0_974:
	s_or_b64 exec, exec, s[0:1]
	s_mov_b64 s[0:1], 0
	s_barrier
	v_readlane_b32 s3, v255, 59
	s_nop 0
	s_add_i32 s3, s3, 1
	v_writelane_b32 v255, s3, 59

; #define LAS __attribute__((address_space(3)))
; __global__ void __launch_bounds__(512) fwd_megakernel(Params P) {
;   extern __shared__ __attribute__((aligned(16))) unsigned char shm[];
;   LAS unsigned char* lds = (LAS unsigned char*)shm;
	.amdhsa_kernel _Z14fwd_megakernel6Params
		.amdhsa_group_segment_fixed_size 2048
		.amdhsa_private_segment_fixed_size 0
		.amdhsa_kernarg_size 472
		.amdhsa_user_sgpr_count 2
		.amdhsa_user_sgpr_dispatch_ptr 0
		.amdhsa_user_sgpr_queue_ptr 0
		.amdhsa_user_sgpr_kernarg_segment_ptr 1
		.amdhsa_user_sgpr_dispatch_id 0
		.amdhsa_user_sgpr_kernarg_preload_length 0
		.amdhsa_user_sgpr_kernarg_preload_offset 0
		.amdhsa_user_sgpr_private_segment_size 0
		.amdhsa_uses_dynamic_stack 0
		.amdhsa_enable_private_segment 0
		.amdhsa_system_sgpr_workgroup_id_x 1
		.amdhsa_system_sgpr_workgroup_id_y 0
		.amdhsa_system_sgpr_workgroup_id_z 0
		.amdhsa_system_sgpr_workgroup_info 0
		.amdhsa_system_vgpr_workitem_id 2
		.amdhsa_next_free_vgpr 256
		.amdhsa_next_free_sgpr 100
		.amdhsa_accum_offset 256
		.amdhsa_reserve_vcc 1
		.amdhsa_float_round_mode_32 0
		.amdhsa_float_round_mode_16_64 0
		.amdhsa_float_denorm_mode_32 3
		.amdhsa_float_denorm_mode_16_64 3
		.amdhsa_dx10_clamp 1
		.amdhsa_ieee_mode 1
		.amdhsa_fp16_overflow 0
		.amdhsa_tg_split 0
		.amdhsa_exception_fp_ieee_invalid_op 0
		.amdhsa_exception_fp_denorm_src 0
		.amdhsa_exception_fp_ieee_div_zero 0
		.amdhsa_exception_fp_ieee_overflow 0
		.amdhsa_exception_fp_ieee_underflow 0
		.amdhsa_exception_fp_ieee_inexact 0
		.amdhsa_exception_int_div_zero 0
	.end_amdhsa_kernel

; #define LAS __attribute__((address_space(3)))
; __global__ void __launch_bounds__(512) fwd_megakernel(Params P) {
;   extern __shared__ __attribute__((aligned(16))) unsigned char shm[];
;   LAS unsigned char* lds = (LAS unsigned char*)shm;
amdhsa.kernels:
  - .agpr_count:     0
    .args:
      - .offset:         0
        .size:           216
        .value_kind:     by_value
      - .offset:         216
        .size:           4
        .value_kind:     hidden_block_count_x
      - .offset:         220
        .size:           4
        .value_kind:     hidden_block_count_y
      - .offset:         224
        .size:           4
        .value_kind:     hidden_block_count_z
      - .offset:         228
        .size:           2
        .value_kind:     hidden_group_size_x
      - .offset:         230
        .size:           2
        .value_kind:     hidden_group_size_y
      - .offset:         232
        .size:           2
        .value_kind:     hidden_group_size_z
      - .offset:         234
        .size:           2
        .value_kind:     hidden_remainder_x
      - .offset:         236
        .size:           2
        .value_kind:     hidden_remainder_y
      - .offset:         238
        .size:           2
        .value_kind:     hidden_remainder_z
      - .offset:         256
        .size:           8
        .value_kind:     hidden_global_offset_x
      - .offset:         264
        .size:           8
        .value_kind:     hidden_global_offset_y
      - .offset:         272
        .size:           8
        .value_kind:     hidden_global_offset_z
      - .offset:         280
        .size:           2
        .value_kind:     hidden_grid_dims
      - .offset:         304
        .size:           8
        .value_kind:     hidden_multigrid_sync_arg
      - .offset:         336
        .size:           4
        .value_kind:     hidden_dynamic_lds_size
    .group_segment_fixed_size: 2048
    .kernarg_segment_align: 8
    .kernarg_segment_size: 472
    .language:       OpenCL C
    .language_version:
      - 2
      - 0
    .max_flat_workgroup_size: 512
    .name:           _Z14fwd_megakernel6Params
    .private_segment_fixed_size: 0
    .sgpr_count:     106
    .sgpr_spill_count: 171
    .symbol:         _Z14fwd_megakernel6Params.kd
    .uniform_work_group_size: 1
    .uses_dynamic_stack: false
    .vgpr_count:     256
    .vgpr_spill_count: 0
    .wavefront_size: 64
